# adds hand-written P1 gates/silu fast paths and latency-hidden rstd_table to the 16B-epilogue version
# speedup vs baseline: 1.0572x; 1.0077x over previous
.LBB0_149:
	s_mov_b64 s[8:9], s[74:75]
	s_load_dwordx2 s[36:37], s[8:9], 0x90
	v_mov_b32_e32 v0, v237
	v_mov_b32_e32 v1, v237
	s_xor_b64 s[0:1], s[0:1], -1
	v_and_b32_e32 v2, 0xff, v1
	v_ashrrev_i32_e32 v4, 8, v1
	v_lshlrev_b32_e32 v0, 2, v2
	v_lshl_or_b32 v0, v4, 10, v0
	v_readlane_b32 s2, v253, 25
	v_writelane_b32 v254, s0, 18
	s_nop 0
	v_add_u32_e32 v3, s2, v0
	v_mov_b64_e32 v[0:1], s[82:83]
	v_writelane_b32 v254, s1, 19
	s_waitcnt lgkmcnt(0)
	s_add_u32 s0, s36, 0x3c00000
	v_mad_i64_i32 v[0:1], s[2:3], s58, v4, v[0:1]
	s_addc_u32 s1, s37, 0
	s_mov_b64 s[2:3], 0
	v_readfirstlane_b32 s5, v0
	v_lshlrev_b32_e32 v5, 6, v2
	s_mov_b32 s4, 0
	s_cmp_lt_u32 s5, 0x880
	s_cselect_b32 s6, s5, 0
	s_cselect_b32 s7, 1, 0
	s_lshl_b32 s7, s7, 0
	s_or_b32 s4, s4, s7
	s_and_b32 s7, s6, 7
	s_lshr_b32 s6, s6, 3
	s_mul_i32 s7, s7, 0x110
	s_add_i32 s6, s6, s7
	s_mul_i32 s7, s6, 0x1e1f
	s_lshr_b32 s7, s7, 20
	s_mul_i32 s10, s7, 0x88
	s_sub_i32 s6, s6, s10
	s_and_b32 s6, s6, 7
	s_lshl_b32 s7, s7, 3
	s_add_i32 s6, s6, s7
	s_lshl_b32 s6, s6, 14
	v_add_u32_e32 v6, s6, v5
	global_load_dwordx4 v[20:23], v6, s[0:1]
	global_load_dwordx4 v[24:27], v6, s[0:1] offset:16
	global_load_dwordx4 v[28:31], v6, s[0:1] offset:32
	global_load_dwordx4 v[32:35], v6, s[0:1] offset:48
	s_add_i32 s5, s5, s40
	s_cmp_lt_u32 s5, 0x880
	s_cselect_b32 s6, s5, 0
	s_cselect_b32 s7, 1, 0
	s_lshl_b32 s7, s7, 1
	s_or_b32 s4, s4, s7
	s_and_b32 s7, s6, 7
	s_lshr_b32 s6, s6, 3
	s_mul_i32 s7, s7, 0x110
	s_add_i32 s6, s6, s7
	s_mul_i32 s7, s6, 0x1e1f
	s_lshr_b32 s7, s7, 20
	s_mul_i32 s10, s7, 0x88
	s_sub_i32 s6, s6, s10
	s_and_b32 s6, s6, 7
	s_lshl_b32 s7, s7, 3
	s_add_i32 s6, s6, s7
	s_lshl_b32 s6, s6, 14
	v_add_u32_e32 v7, s6, v5
	global_load_dwordx4 v[36:39], v7, s[0:1]
	global_load_dwordx4 v[40:43], v7, s[0:1] offset:16
	global_load_dwordx4 v[44:47], v7, s[0:1] offset:32
	global_load_dwordx4 v[48:51], v7, s[0:1] offset:48
	s_add_i32 s5, s5, s40
	s_cmp_lt_u32 s5, 0x880
	s_cselect_b32 s6, s5, 0
	s_cselect_b32 s7, 1, 0
	s_lshl_b32 s7, s7, 2
	s_or_b32 s4, s4, s7
	s_and_b32 s7, s6, 7
	s_lshr_b32 s6, s6, 3
	s_mul_i32 s7, s7, 0x110
	s_add_i32 s6, s6, s7
	s_mul_i32 s7, s6, 0x1e1f
	s_lshr_b32 s7, s7, 20
	s_mul_i32 s10, s7, 0x88
	s_sub_i32 s6, s6, s10
	s_and_b32 s6, s6, 7
	s_lshl_b32 s7, s7, 3
	s_add_i32 s6, s6, s7
	s_lshl_b32 s6, s6, 14
	v_add_u32_e32 v8, s6, v5
	global_load_dwordx4 v[52:55], v8, s[0:1]
	global_load_dwordx4 v[56:59], v8, s[0:1] offset:16
	global_load_dwordx4 v[60:63], v8, s[0:1] offset:32
	global_load_dwordx4 v[64:67], v8, s[0:1] offset:48
	s_add_i32 s5, s5, s40
	s_cmp_lt_u32 s5, 0x880
	s_cselect_b32 s6, s5, 0
	s_cselect_b32 s7, 1, 0
	s_lshl_b32 s7, s7, 3
	s_or_b32 s4, s4, s7
	s_and_b32 s7, s6, 7
	s_lshr_b32 s6, s6, 3
	s_mul_i32 s7, s7, 0x110
	s_add_i32 s6, s6, s7
	s_mul_i32 s7, s6, 0x1e1f
	s_lshr_b32 s7, s7, 20
	s_mul_i32 s10, s7, 0x88
	s_sub_i32 s6, s6, s10
	s_and_b32 s6, s6, 7
	s_lshl_b32 s7, s7, 3
	s_add_i32 s6, s6, s7
	s_lshl_b32 s6, s6, 14
	v_add_u32_e32 v9, s6, v5
	global_load_dwordx4 v[68:71], v9, s[0:1]
	global_load_dwordx4 v[72:75], v9, s[0:1] offset:16
	global_load_dwordx4 v[76:79], v9, s[0:1] offset:32
	global_load_dwordx4 v[80:83], v9, s[0:1] offset:48
	s_add_i32 s5, s5, s40
	s_cmp_lt_u32 s5, 0x880
	s_cselect_b32 s6, s5, 0
	s_cselect_b32 s7, 1, 0
	s_lshl_b32 s7, s7, 4
	s_or_b32 s4, s4, s7
	s_and_b32 s7, s6, 7
	s_lshr_b32 s6, s6, 3
	s_mul_i32 s7, s7, 0x110
	s_add_i32 s6, s6, s7
	s_mul_i32 s7, s6, 0x1e1f
	s_lshr_b32 s7, s7, 20
	s_mul_i32 s10, s7, 0x88
	s_sub_i32 s6, s6, s10
	s_and_b32 s6, s6, 7
	s_lshl_b32 s7, s7, 3
	s_add_i32 s6, s6, s7
	s_lshl_b32 s6, s6, 14
	v_add_u32_e32 v10, s6, v5
	global_load_dwordx4 v[84:87], v10, s[0:1]
	global_load_dwordx4 v[88:91], v10, s[0:1] offset:16
	global_load_dwordx4 v[92:95], v10, s[0:1] offset:32
	global_load_dwordx4 v[96:99], v10, s[0:1] offset:48
	s_add_i32 s5, s5, s40
	s_cmp_lt_u32 s5, 0x880
	s_cselect_b32 s6, s5, 0
	s_cselect_b32 s7, 1, 0
	s_lshl_b32 s7, s7, 5
	s_or_b32 s4, s4, s7
	s_and_b32 s7, s6, 7
	s_lshr_b32 s6, s6, 3
	s_mul_i32 s7, s7, 0x110
	s_add_i32 s6, s6, s7
	s_mul_i32 s7, s6, 0x1e1f
	s_lshr_b32 s7, s7, 20
	s_mul_i32 s10, s7, 0x88
	s_sub_i32 s6, s6, s10
	s_and_b32 s6, s6, 7
	s_lshl_b32 s7, s7, 3
	s_add_i32 s6, s6, s7
	s_lshl_b32 s6, s6, 14
	v_add_u32_e32 v11, s6, v5
	global_load_dwordx4 v[100:103], v11, s[0:1]
	global_load_dwordx4 v[104:107], v11, s[0:1] offset:16
	global_load_dwordx4 v[108:111], v11, s[0:1] offset:32
	global_load_dwordx4 v[112:115], v11, s[0:1] offset:48
	s_waitcnt vmcnt(20)
	v_pk_add_f32 v[22:23], v[22:23], v[26:27]
	v_pk_add_f32 v[20:21], v[20:21], v[24:25]
	v_pk_add_f32 v[24:25], v[30:31], v[34:35]
	v_pk_add_f32 v[26:27], v[28:29], v[32:33]
	v_pk_add_f32 v[22:23], v[22:23], v[24:25]
	v_pk_add_f32 v[20:21], v[20:21], v[26:27]
	s_nop 0
	v_pk_mov_b32 v[24:25], v[20:21], v[22:23] op_sel:[1,0]
	v_mov_b32_e32 v21, v23
	v_pk_add_f32 v[20:21], v[24:25], v[20:21]
	s_nop 0
	v_add_f32_e32 v20, v20, v21
	v_fmamk_f32 v20, v20, 0x3a800000, v234
	v_mul_f32_e32 v21, 0x4b800000, v20
	v_cmp_gt_f32_e32 vcc, 0x800000, v20
	s_nop 1
	v_cndmask_b32_e32 v20, v20, v21, vcc
	v_rsq_f32_e32 v20, v20
	s_nop 0
	v_mul_f32_e32 v21, 0x45800000, v20
	v_cndmask_b32_e32 v20, v20, v21, vcc
	s_bitcmp1_b32 s4, 0
	s_cbranch_scc0 .Lrta_s0
	ds_write_b32 v3, v20
.Lrta_s0:
	v_add_u32_e32 v3, 0x800, v3
	s_waitcnt vmcnt(16)
	v_pk_add_f32 v[38:39], v[38:39], v[42:43]
	v_pk_add_f32 v[36:37], v[36:37], v[40:41]
	v_pk_add_f32 v[40:41], v[46:47], v[50:51]
	v_pk_add_f32 v[42:43], v[44:45], v[48:49]
	v_pk_add_f32 v[38:39], v[38:39], v[40:41]
	v_pk_add_f32 v[36:37], v[36:37], v[42:43]
	s_nop 0
	v_pk_mov_b32 v[40:41], v[36:37], v[38:39] op_sel:[1,0]
	v_mov_b32_e32 v37, v39
	v_pk_add_f32 v[36:37], v[40:41], v[36:37]
	s_nop 0
	v_add_f32_e32 v36, v36, v37
	v_fmamk_f32 v36, v36, 0x3a800000, v234
	v_mul_f32_e32 v37, 0x4b800000, v36
	v_cmp_gt_f32_e32 vcc, 0x800000, v36
	s_nop 1
	v_cndmask_b32_e32 v36, v36, v37, vcc
	v_rsq_f32_e32 v36, v36
	s_nop 0
	v_mul_f32_e32 v37, 0x45800000, v36
	v_cndmask_b32_e32 v36, v36, v37, vcc
	s_bitcmp1_b32 s4, 1
	s_cbranch_scc0 .Lrta_s1
	ds_write_b32 v3, v36
.Lrta_s1:
	v_add_u32_e32 v3, 0x800, v3
	s_waitcnt vmcnt(12)
	v_pk_add_f32 v[54:55], v[54:55], v[58:59]
	v_pk_add_f32 v[52:53], v[52:53], v[56:57]
	v_pk_add_f32 v[56:57], v[62:63], v[66:67]
	v_pk_add_f32 v[58:59], v[60:61], v[64:65]
	v_pk_add_f32 v[54:55], v[54:55], v[56:57]
	v_pk_add_f32 v[52:53], v[52:53], v[58:59]
	s_nop 0
	v_pk_mov_b32 v[56:57], v[52:53], v[54:55] op_sel:[1,0]
	v_mov_b32_e32 v53, v55
	v_pk_add_f32 v[52:53], v[56:57], v[52:53]
	s_nop 0
	v_add_f32_e32 v52, v52, v53
	v_fmamk_f32 v52, v52, 0x3a800000, v234
	v_mul_f32_e32 v53, 0x4b800000, v52
	v_cmp_gt_f32_e32 vcc, 0x800000, v52
	s_nop 1
	v_cndmask_b32_e32 v52, v52, v53, vcc
	v_rsq_f32_e32 v52, v52
	s_nop 0
	v_mul_f32_e32 v53, 0x45800000, v52
	v_cndmask_b32_e32 v52, v52, v53, vcc
	s_bitcmp1_b32 s4, 2
	s_cbranch_scc0 .Lrta_s2
	ds_write_b32 v3, v52
.Lrta_s2:
	v_add_u32_e32 v3, 0x800, v3
	s_waitcnt vmcnt(8)
	v_pk_add_f32 v[70:71], v[70:71], v[74:75]
	v_pk_add_f32 v[68:69], v[68:69], v[72:73]
	v_pk_add_f32 v[72:73], v[78:79], v[82:83]
	v_pk_add_f32 v[74:75], v[76:77], v[80:81]
	v_pk_add_f32 v[70:71], v[70:71], v[72:73]
	v_pk_add_f32 v[68:69], v[68:69], v[74:75]
	s_nop 0
	v_pk_mov_b32 v[72:73], v[68:69], v[70:71] op_sel:[1,0]
	v_mov_b32_e32 v69, v71
	v_pk_add_f32 v[68:69], v[72:73], v[68:69]
	s_nop 0
	v_add_f32_e32 v68, v68, v69
	v_fmamk_f32 v68, v68, 0x3a800000, v234
	v_mul_f32_e32 v69, 0x4b800000, v68
	v_cmp_gt_f32_e32 vcc, 0x800000, v68
	s_nop 1
	v_cndmask_b32_e32 v68, v68, v69, vcc
	v_rsq_f32_e32 v68, v68
	s_nop 0
	v_mul_f32_e32 v69, 0x45800000, v68
	v_cndmask_b32_e32 v68, v68, v69, vcc
	s_bitcmp1_b32 s4, 3
	s_cbranch_scc0 .Lrta_s3
	ds_write_b32 v3, v68
.Lrta_s3:
	v_add_u32_e32 v3, 0x800, v3
	s_waitcnt vmcnt(4)
	v_pk_add_f32 v[86:87], v[86:87], v[90:91]
	v_pk_add_f32 v[84:85], v[84:85], v[88:89]
	v_pk_add_f32 v[88:89], v[94:95], v[98:99]
	v_pk_add_f32 v[90:91], v[92:93], v[96:97]
	v_pk_add_f32 v[86:87], v[86:87], v[88:89]
	v_pk_add_f32 v[84:85], v[84:85], v[90:91]
	s_nop 0
	v_pk_mov_b32 v[88:89], v[84:85], v[86:87] op_sel:[1,0]
	v_mov_b32_e32 v85, v87
	v_pk_add_f32 v[84:85], v[88:89], v[84:85]
	s_nop 0
	v_add_f32_e32 v84, v84, v85
	v_fmamk_f32 v84, v84, 0x3a800000, v234
	v_mul_f32_e32 v85, 0x4b800000, v84
	v_cmp_gt_f32_e32 vcc, 0x800000, v84
	s_nop 1
	v_cndmask_b32_e32 v84, v84, v85, vcc
	v_rsq_f32_e32 v84, v84
	s_nop 0
	v_mul_f32_e32 v85, 0x45800000, v84
	v_cndmask_b32_e32 v84, v84, v85, vcc
	s_bitcmp1_b32 s4, 4
	s_cbranch_scc0 .Lrta_s4
	ds_write_b32 v3, v84
.Lrta_s4:
	v_add_u32_e32 v3, 0x800, v3
	s_waitcnt vmcnt(0)
	v_pk_add_f32 v[102:103], v[102:103], v[106:107]
	v_pk_add_f32 v[100:101], v[100:101], v[104:105]
	v_pk_add_f32 v[104:105], v[110:111], v[114:115]
	v_pk_add_f32 v[106:107], v[108:109], v[112:113]
	v_pk_add_f32 v[102:103], v[102:103], v[104:105]
	v_pk_add_f32 v[100:101], v[100:101], v[106:107]
	s_nop 0
	v_pk_mov_b32 v[104:105], v[100:101], v[102:103] op_sel:[1,0]
	v_mov_b32_e32 v101, v103
	v_pk_add_f32 v[100:101], v[104:105], v[100:101]
	s_nop 0
	v_add_f32_e32 v100, v100, v101
	v_fmamk_f32 v100, v100, 0x3a800000, v234
	v_mul_f32_e32 v101, 0x4b800000, v100
	v_cmp_gt_f32_e32 vcc, 0x800000, v100
	s_nop 1
	v_cndmask_b32_e32 v100, v100, v101, vcc
	v_rsq_f32_e32 v100, v100
	s_nop 0
	v_mul_f32_e32 v101, 0x45800000, v100
	v_cndmask_b32_e32 v100, v100, v101, vcc
	s_bitcmp1_b32 s4, 5
	s_cbranch_scc0 .Lrta_s5
	ds_write_b32 v3, v100
.Lrta_s5:
	v_add_u32_e32 v3, 0x800, v3

.LBB0_182:
	s_cmp_gt_i32 s55, 6
	s_cbranch_scc1 .Lp1f_start
	s_lshl_b32 s12, s60, 10
	s_add_i32 s12, s4, s12
	v_lshl_add_u32 v16, v193, 2, s12
	ds_read2_b32 v[180:181], v16 offset1:16
	ds_read2_b32 v[178:179], v16 offset0:32 offset1:48
	ds_read2_b32 v[176:177], v16 offset0:128 offset1:144
	ds_read2_b32 v[172:173], v16 offset0:160 offset1:176
	s_cmp_lg_u32 s55, 4
	s_cbranch_scc1 .LBB0_184
	global_load_dword v192, v201, s[50:51]
	global_load_dword v191, v201, s[50:51] offset:16
	s_branch .LBB0_185

.Lp1f_start:
	s_lshl_b32 s12, s60, 10
	s_add_i32 s12, s4, s12
	v_lshl_add_u32 v184, v186, 2, s12
	ds_read2_b32 v[202:203], v184 offset1:16
	ds_read2_b32 v[204:205], v184 offset0:32 offset1:48
	ds_read2_b32 v[206:207], v184 offset0:128 offset1:144
	ds_read2_b32 v[208:209], v184 offset0:160 offset1:176
	s_cmp_gt_i32 s55, 8
	s_cbranch_scc0 .Lp1f_silu
	v_readlane_b32 s36, v254, 32
	s_add_i32 s16, s55, -9
	s_lshl_b32 s16, s16, 10
	s_mov_b32 s37, s8
	s_add_u32 s36, s36, s16
	s_addc_u32 s37, s37, 0
	v_lshlrev_b32_e32 v185, 4, v187
	global_load_dwordx4 v[168:171], v185, s[36:37]
	global_load_dwordx4 v[172:175], v185, s[36:37] offset:64
	global_load_dwordx4 v[176:179], v185, s[36:37] offset:512
	global_load_dwordx4 v[180:183], v185, s[36:37] offset:576
	s_lshl_b32 s12, s64, 8
	s_add_i32 s12, s12, s94
	v_add_u32_e32 v196, s12, v186
	v_lshlrev_b32_e32 v196, 12, v196
	s_add_i32 s12, s55, -9
	s_lshl_b32 s12, s12, 8
	s_add_i32 s12, s12, s24
	s_lshl_b32 s12, s12, 1
	v_and_b32_e32 v197, 1, v187
	v_lshlrev_b32_e32 v198, 3, v187
	v_mad_u32_u24 v197, v197, 24, v198
	v_add3_u32 v196, v196, v197, s12
	v_mov_b32_e32 v197, 0
	v_lshl_add_u64 v[196:197], v[196:197], 0, s[22:23]
	s_mov_b32 s13, 0
	s_waitcnt vmcnt(0) lgkmcnt(0)
	s_mov_b32 s12, 0x0
	v_lshl_add_u64 v[198:199], v[196:197], 0, s[12:13]
	v_mul_f32_e32 v148, v148, v202
	v_mul_f32_e32 v149, v149, v202
	v_mul_f32_e32 v150, v150, v202
	v_mul_f32_e32 v151, v151, v202
	v_mul_f32_e32 v156, v156, v202
	v_mul_f32_e32 v157, v157, v202
	v_mul_f32_e32 v158, v158, v202
	v_mul_f32_e32 v159, v159, v202
	v_add_f32_e32 v148, v148, v168
	v_add_f32_e32 v149, v149, v169
	v_add_f32_e32 v150, v150, v170
	v_add_f32_e32 v151, v151, v171
	v_add_f32_e32 v156, v156, v172
	v_add_f32_e32 v157, v157, v173
	v_add_f32_e32 v158, v158, v174
	v_add_f32_e32 v159, v159, v175
	v_mul_f32_e32 v148, 0xbfb8aa3b, v148
	v_mul_f32_e32 v149, 0xbfb8aa3b, v149
	v_mul_f32_e32 v150, 0xbfb8aa3b, v150
	v_mul_f32_e32 v151, 0xbfb8aa3b, v151
	v_mul_f32_e32 v156, 0xbfb8aa3b, v156
	v_mul_f32_e32 v157, 0xbfb8aa3b, v157
	v_mul_f32_e32 v158, 0xbfb8aa3b, v158
	v_mul_f32_e32 v159, 0xbfb8aa3b, v159
	v_exp_f32_e32 v148, v148
	v_exp_f32_e32 v149, v149
	v_exp_f32_e32 v150, v150
	v_exp_f32_e32 v151, v151
	v_exp_f32_e32 v156, v156
	v_exp_f32_e32 v157, v157
	v_exp_f32_e32 v158, v158
	v_exp_f32_e32 v159, v159
	v_add_f32_e32 v148, 1.0, v148
	v_add_f32_e32 v149, 1.0, v149
	v_add_f32_e32 v150, 1.0, v150
	v_add_f32_e32 v151, 1.0, v151
	v_add_f32_e32 v156, 1.0, v156
	v_add_f32_e32 v157, 1.0, v157
	v_add_f32_e32 v158, 1.0, v158
	v_add_f32_e32 v159, 1.0, v159
	v_rcp_f32_e32 v148, v148
	v_rcp_f32_e32 v149, v149
	v_rcp_f32_e32 v150, v150
	v_rcp_f32_e32 v151, v151
	v_rcp_f32_e32 v156, v156
	v_rcp_f32_e32 v157, v157
	v_rcp_f32_e32 v158, v158
	v_rcp_f32_e32 v159, v159
	s_nop 0
	v_cvt_pk_bf16_f32 v148, v148, v149
	v_cvt_pk_bf16_f32 v149, v150, v151
	v_cvt_pk_bf16_f32 v150, v156, v157
	v_cvt_pk_bf16_f32 v151, v158, v159
	s_nop 1
	v_permlane16_swap_b32_e32 v148, v150
	v_permlane16_swap_b32_e32 v149, v151
	global_store_dwordx4 v[198:199], v[148:151], off
	v_mul_f32_e32 v144, v144, v202
	v_mul_f32_e32 v145, v145, v202
	v_mul_f32_e32 v146, v146, v202
	v_mul_f32_e32 v147, v147, v202
	v_mul_f32_e32 v152, v152, v202
	v_mul_f32_e32 v153, v153, v202
	v_mul_f32_e32 v154, v154, v202
	v_mul_f32_e32 v155, v155, v202
	v_add_f32_e32 v144, v144, v176
	v_add_f32_e32 v145, v145, v177
	v_add_f32_e32 v146, v146, v178
	v_add_f32_e32 v147, v147, v179
	v_add_f32_e32 v152, v152, v180
	v_add_f32_e32 v153, v153, v181
	v_add_f32_e32 v154, v154, v182
	v_add_f32_e32 v155, v155, v183
	v_mul_f32_e32 v144, 0xbfb8aa3b, v144
	v_mul_f32_e32 v145, 0xbfb8aa3b, v145
	v_mul_f32_e32 v146, 0xbfb8aa3b, v146
	v_mul_f32_e32 v147, 0xbfb8aa3b, v147
	v_mul_f32_e32 v152, 0xbfb8aa3b, v152
	v_mul_f32_e32 v153, 0xbfb8aa3b, v153
	v_mul_f32_e32 v154, 0xbfb8aa3b, v154
	v_mul_f32_e32 v155, 0xbfb8aa3b, v155
	v_exp_f32_e32 v144, v144
	v_exp_f32_e32 v145, v145
	v_exp_f32_e32 v146, v146
	v_exp_f32_e32 v147, v147
	v_exp_f32_e32 v152, v152
	v_exp_f32_e32 v153, v153
	v_exp_f32_e32 v154, v154
	v_exp_f32_e32 v155, v155
	v_add_f32_e32 v144, 1.0, v144
	v_add_f32_e32 v145, 1.0, v145
	v_add_f32_e32 v146, 1.0, v146
	v_add_f32_e32 v147, 1.0, v147
	v_add_f32_e32 v152, 1.0, v152
	v_add_f32_e32 v153, 1.0, v153
	v_add_f32_e32 v154, 1.0, v154
	v_add_f32_e32 v155, 1.0, v155
	v_rcp_f32_e32 v144, v144
	v_rcp_f32_e32 v145, v145
	v_rcp_f32_e32 v146, v146
	v_rcp_f32_e32 v147, v147
	v_rcp_f32_e32 v152, v152
	v_rcp_f32_e32 v153, v153
	v_rcp_f32_e32 v154, v154
	v_rcp_f32_e32 v155, v155
	s_nop 0
	v_cvt_pk_bf16_f32 v144, v144, v145
	v_cvt_pk_bf16_f32 v145, v146, v147
	v_cvt_pk_bf16_f32 v146, v152, v153
	v_cvt_pk_bf16_f32 v147, v154, v155
	s_nop 1
	v_permlane16_swap_b32_e32 v144, v146
	v_permlane16_swap_b32_e32 v145, v147
	global_store_dwordx4 v[198:199], v[144:147], off offset:256
	s_nop 0
	s_mov_b32 s12, 0x10000
	v_lshl_add_u64 v[198:199], v[196:197], 0, s[12:13]
	v_mul_f32_e32 v140, v140, v203
	v_mul_f32_e32 v141, v141, v203
	v_mul_f32_e32 v142, v142, v203
	v_mul_f32_e32 v143, v143, v203
	v_mul_f32_e32 v136, v136, v203
	v_mul_f32_e32 v137, v137, v203
	v_mul_f32_e32 v138, v138, v203
	v_mul_f32_e32 v139, v139, v203
	v_add_f32_e32 v140, v140, v168
	v_add_f32_e32 v141, v141, v169
	v_add_f32_e32 v142, v142, v170
	v_add_f32_e32 v143, v143, v171
	v_add_f32_e32 v136, v136, v172
	v_add_f32_e32 v137, v137, v173
	v_add_f32_e32 v138, v138, v174
	v_add_f32_e32 v139, v139, v175
	v_mul_f32_e32 v140, 0xbfb8aa3b, v140
	v_mul_f32_e32 v141, 0xbfb8aa3b, v141
	v_mul_f32_e32 v142, 0xbfb8aa3b, v142
	v_mul_f32_e32 v143, 0xbfb8aa3b, v143
	v_mul_f32_e32 v136, 0xbfb8aa3b, v136
	v_mul_f32_e32 v137, 0xbfb8aa3b, v137
	v_mul_f32_e32 v138, 0xbfb8aa3b, v138
	v_mul_f32_e32 v139, 0xbfb8aa3b, v139
	v_exp_f32_e32 v140, v140
	v_exp_f32_e32 v141, v141
	v_exp_f32_e32 v142, v142
	v_exp_f32_e32 v143, v143
	v_exp_f32_e32 v136, v136
	v_exp_f32_e32 v137, v137
	v_exp_f32_e32 v138, v138
	v_exp_f32_e32 v139, v139
	v_add_f32_e32 v140, 1.0, v140
	v_add_f32_e32 v141, 1.0, v141
	v_add_f32_e32 v142, 1.0, v142
	v_add_f32_e32 v143, 1.0, v143
	v_add_f32_e32 v136, 1.0, v136
	v_add_f32_e32 v137, 1.0, v137
	v_add_f32_e32 v138, 1.0, v138
	v_add_f32_e32 v139, 1.0, v139
	v_rcp_f32_e32 v140, v140
	v_rcp_f32_e32 v141, v141
	v_rcp_f32_e32 v142, v142
	v_rcp_f32_e32 v143, v143
	v_rcp_f32_e32 v136, v136
	v_rcp_f32_e32 v137, v137
	v_rcp_f32_e32 v138, v138
	v_rcp_f32_e32 v139, v139
	s_nop 0
	v_cvt_pk_bf16_f32 v140, v140, v141
	v_cvt_pk_bf16_f32 v141, v142, v143
	v_cvt_pk_bf16_f32 v142, v136, v137
	v_cvt_pk_bf16_f32 v143, v138, v139
	s_nop 1
	v_permlane16_swap_b32_e32 v140, v142
	v_permlane16_swap_b32_e32 v141, v143
	global_store_dwordx4 v[198:199], v[140:143], off
	v_mul_f32_e32 v132, v132, v203
	v_mul_f32_e32 v133, v133, v203
	v_mul_f32_e32 v134, v134, v203
	v_mul_f32_e32 v135, v135, v203
	v_mul_f32_e32 v128, v128, v203
	v_mul_f32_e32 v129, v129, v203
	v_mul_f32_e32 v130, v130, v203
	v_mul_f32_e32 v131, v131, v203
	v_add_f32_e32 v132, v132, v176
	v_add_f32_e32 v133, v133, v177
	v_add_f32_e32 v134, v134, v178
	v_add_f32_e32 v135, v135, v179
	v_add_f32_e32 v128, v128, v180
	v_add_f32_e32 v129, v129, v181
	v_add_f32_e32 v130, v130, v182
	v_add_f32_e32 v131, v131, v183
	v_mul_f32_e32 v132, 0xbfb8aa3b, v132
	v_mul_f32_e32 v133, 0xbfb8aa3b, v133
	v_mul_f32_e32 v134, 0xbfb8aa3b, v134
	v_mul_f32_e32 v135, 0xbfb8aa3b, v135
	v_mul_f32_e32 v128, 0xbfb8aa3b, v128
	v_mul_f32_e32 v129, 0xbfb8aa3b, v129
	v_mul_f32_e32 v130, 0xbfb8aa3b, v130
	v_mul_f32_e32 v131, 0xbfb8aa3b, v131
	v_exp_f32_e32 v132, v132
	v_exp_f32_e32 v133, v133
	v_exp_f32_e32 v134, v134
	v_exp_f32_e32 v135, v135
	v_exp_f32_e32 v128, v128
	v_exp_f32_e32 v129, v129
	v_exp_f32_e32 v130, v130
	v_exp_f32_e32 v131, v131
	v_add_f32_e32 v132, 1.0, v132
	v_add_f32_e32 v133, 1.0, v133
	v_add_f32_e32 v134, 1.0, v134
	v_add_f32_e32 v135, 1.0, v135
	v_add_f32_e32 v128, 1.0, v128
	v_add_f32_e32 v129, 1.0, v129
	v_add_f32_e32 v130, 1.0, v130
	v_add_f32_e32 v131, 1.0, v131
	v_rcp_f32_e32 v132, v132
	v_rcp_f32_e32 v133, v133
	v_rcp_f32_e32 v134, v134
	v_rcp_f32_e32 v135, v135
	v_rcp_f32_e32 v128, v128
	v_rcp_f32_e32 v129, v129
	v_rcp_f32_e32 v130, v130
	v_rcp_f32_e32 v131, v131
	s_nop 0
	v_cvt_pk_bf16_f32 v132, v132, v133
	v_cvt_pk_bf16_f32 v133, v134, v135
	v_cvt_pk_bf16_f32 v134, v128, v129
	v_cvt_pk_bf16_f32 v135, v130, v131
	s_nop 1
	v_permlane16_swap_b32_e32 v132, v134
	v_permlane16_swap_b32_e32 v133, v135
	global_store_dwordx4 v[198:199], v[132:135], off offset:256
	s_nop 0
	s_mov_b32 s12, 0x20000
	v_lshl_add_u64 v[198:199], v[196:197], 0, s[12:13]
	v_mul_f32_e32 v124, v124, v204
	v_mul_f32_e32 v125, v125, v204
	v_mul_f32_e32 v126, v126, v204
	v_mul_f32_e32 v127, v127, v204
	v_mul_f32_e32 v120, v120, v204
	v_mul_f32_e32 v121, v121, v204
	v_mul_f32_e32 v122, v122, v204
	v_mul_f32_e32 v123, v123, v204
	v_add_f32_e32 v124, v124, v168
	v_add_f32_e32 v125, v125, v169
	v_add_f32_e32 v126, v126, v170
	v_add_f32_e32 v127, v127, v171
	v_add_f32_e32 v120, v120, v172
	v_add_f32_e32 v121, v121, v173
	v_add_f32_e32 v122, v122, v174
	v_add_f32_e32 v123, v123, v175
	v_mul_f32_e32 v124, 0xbfb8aa3b, v124
	v_mul_f32_e32 v125, 0xbfb8aa3b, v125
	v_mul_f32_e32 v126, 0xbfb8aa3b, v126
	v_mul_f32_e32 v127, 0xbfb8aa3b, v127
	v_mul_f32_e32 v120, 0xbfb8aa3b, v120
	v_mul_f32_e32 v121, 0xbfb8aa3b, v121
	v_mul_f32_e32 v122, 0xbfb8aa3b, v122
	v_mul_f32_e32 v123, 0xbfb8aa3b, v123
	v_exp_f32_e32 v124, v124
	v_exp_f32_e32 v125, v125
	v_exp_f32_e32 v126, v126
	v_exp_f32_e32 v127, v127
	v_exp_f32_e32 v120, v120
	v_exp_f32_e32 v121, v121
	v_exp_f32_e32 v122, v122
	v_exp_f32_e32 v123, v123
	v_add_f32_e32 v124, 1.0, v124
	v_add_f32_e32 v125, 1.0, v125
	v_add_f32_e32 v126, 1.0, v126
	v_add_f32_e32 v127, 1.0, v127
	v_add_f32_e32 v120, 1.0, v120
	v_add_f32_e32 v121, 1.0, v121
	v_add_f32_e32 v122, 1.0, v122
	v_add_f32_e32 v123, 1.0, v123
	v_rcp_f32_e32 v124, v124
	v_rcp_f32_e32 v125, v125
	v_rcp_f32_e32 v126, v126
	v_rcp_f32_e32 v127, v127
	v_rcp_f32_e32 v120, v120
	v_rcp_f32_e32 v121, v121
	v_rcp_f32_e32 v122, v122
	v_rcp_f32_e32 v123, v123
	s_nop 0
	v_cvt_pk_bf16_f32 v124, v124, v125
	v_cvt_pk_bf16_f32 v125, v126, v127
	v_cvt_pk_bf16_f32 v126, v120, v121
	v_cvt_pk_bf16_f32 v127, v122, v123
	s_nop 1
	v_permlane16_swap_b32_e32 v124, v126
	v_permlane16_swap_b32_e32 v125, v127
	global_store_dwordx4 v[198:199], v[124:127], off
	v_mul_f32_e32 v116, v116, v204
	v_mul_f32_e32 v117, v117, v204
	v_mul_f32_e32 v118, v118, v204
	v_mul_f32_e32 v119, v119, v204
	v_mul_f32_e32 v112, v112, v204
	v_mul_f32_e32 v113, v113, v204
	v_mul_f32_e32 v114, v114, v204
	v_mul_f32_e32 v115, v115, v204
	v_add_f32_e32 v116, v116, v176
	v_add_f32_e32 v117, v117, v177
	v_add_f32_e32 v118, v118, v178
	v_add_f32_e32 v119, v119, v179
	v_add_f32_e32 v112, v112, v180
	v_add_f32_e32 v113, v113, v181
	v_add_f32_e32 v114, v114, v182
	v_add_f32_e32 v115, v115, v183
	v_mul_f32_e32 v116, 0xbfb8aa3b, v116
	v_mul_f32_e32 v117, 0xbfb8aa3b, v117
	v_mul_f32_e32 v118, 0xbfb8aa3b, v118
	v_mul_f32_e32 v119, 0xbfb8aa3b, v119
	v_mul_f32_e32 v112, 0xbfb8aa3b, v112
	v_mul_f32_e32 v113, 0xbfb8aa3b, v113
	v_mul_f32_e32 v114, 0xbfb8aa3b, v114
	v_mul_f32_e32 v115, 0xbfb8aa3b, v115
	v_exp_f32_e32 v116, v116
	v_exp_f32_e32 v117, v117
	v_exp_f32_e32 v118, v118
	v_exp_f32_e32 v119, v119
	v_exp_f32_e32 v112, v112
	v_exp_f32_e32 v113, v113
	v_exp_f32_e32 v114, v114
	v_exp_f32_e32 v115, v115
	v_add_f32_e32 v116, 1.0, v116
	v_add_f32_e32 v117, 1.0, v117
	v_add_f32_e32 v118, 1.0, v118
	v_add_f32_e32 v119, 1.0, v119
	v_add_f32_e32 v112, 1.0, v112
	v_add_f32_e32 v113, 1.0, v113
	v_add_f32_e32 v114, 1.0, v114
	v_add_f32_e32 v115, 1.0, v115
	v_rcp_f32_e32 v116, v116
	v_rcp_f32_e32 v117, v117
	v_rcp_f32_e32 v118, v118
	v_rcp_f32_e32 v119, v119
	v_rcp_f32_e32 v112, v112
	v_rcp_f32_e32 v113, v113
	v_rcp_f32_e32 v114, v114
	v_rcp_f32_e32 v115, v115
	s_nop 0
	v_cvt_pk_bf16_f32 v116, v116, v117
	v_cvt_pk_bf16_f32 v117, v118, v119
	v_cvt_pk_bf16_f32 v118, v112, v113
	v_cvt_pk_bf16_f32 v119, v114, v115
	s_nop 1
	v_permlane16_swap_b32_e32 v116, v118
	v_permlane16_swap_b32_e32 v117, v119
	global_store_dwordx4 v[198:199], v[116:119], off offset:256
	s_nop 0
	s_mov_b32 s12, 0x30000
	v_lshl_add_u64 v[198:199], v[196:197], 0, s[12:13]
	v_mul_f32_e32 v108, v108, v205
	v_mul_f32_e32 v109, v109, v205
	v_mul_f32_e32 v110, v110, v205
	v_mul_f32_e32 v111, v111, v205
	v_mul_f32_e32 v104, v104, v205
	v_mul_f32_e32 v105, v105, v205
	v_mul_f32_e32 v106, v106, v205
	v_mul_f32_e32 v107, v107, v205
	v_add_f32_e32 v108, v108, v168
	v_add_f32_e32 v109, v109, v169
	v_add_f32_e32 v110, v110, v170
	v_add_f32_e32 v111, v111, v171
	v_add_f32_e32 v104, v104, v172
	v_add_f32_e32 v105, v105, v173
	v_add_f32_e32 v106, v106, v174
	v_add_f32_e32 v107, v107, v175
	v_mul_f32_e32 v108, 0xbfb8aa3b, v108
	v_mul_f32_e32 v109, 0xbfb8aa3b, v109
	v_mul_f32_e32 v110, 0xbfb8aa3b, v110
	v_mul_f32_e32 v111, 0xbfb8aa3b, v111
	v_mul_f32_e32 v104, 0xbfb8aa3b, v104
	v_mul_f32_e32 v105, 0xbfb8aa3b, v105
	v_mul_f32_e32 v106, 0xbfb8aa3b, v106
	v_mul_f32_e32 v107, 0xbfb8aa3b, v107
	v_exp_f32_e32 v108, v108
	v_exp_f32_e32 v109, v109
	v_exp_f32_e32 v110, v110
	v_exp_f32_e32 v111, v111
	v_exp_f32_e32 v104, v104
	v_exp_f32_e32 v105, v105
	v_exp_f32_e32 v106, v106
	v_exp_f32_e32 v107, v107
	v_add_f32_e32 v108, 1.0, v108
	v_add_f32_e32 v109, 1.0, v109
	v_add_f32_e32 v110, 1.0, v110
	v_add_f32_e32 v111, 1.0, v111
	v_add_f32_e32 v104, 1.0, v104
	v_add_f32_e32 v105, 1.0, v105
	v_add_f32_e32 v106, 1.0, v106
	v_add_f32_e32 v107, 1.0, v107
	v_rcp_f32_e32 v108, v108
	v_rcp_f32_e32 v109, v109
	v_rcp_f32_e32 v110, v110
	v_rcp_f32_e32 v111, v111
	v_rcp_f32_e32 v104, v104
	v_rcp_f32_e32 v105, v105
	v_rcp_f32_e32 v106, v106
	v_rcp_f32_e32 v107, v107
	s_nop 0
	v_cvt_pk_bf16_f32 v108, v108, v109
	v_cvt_pk_bf16_f32 v109, v110, v111
	v_cvt_pk_bf16_f32 v110, v104, v105
	v_cvt_pk_bf16_f32 v111, v106, v107
	s_nop 1
	v_permlane16_swap_b32_e32 v108, v110
	v_permlane16_swap_b32_e32 v109, v111
	global_store_dwordx4 v[198:199], v[108:111], off
	v_mul_f32_e32 v100, v100, v205
	v_mul_f32_e32 v101, v101, v205
	v_mul_f32_e32 v102, v102, v205
	v_mul_f32_e32 v103, v103, v205
	v_mul_f32_e32 v96, v96, v205
	v_mul_f32_e32 v97, v97, v205
	v_mul_f32_e32 v98, v98, v205
	v_mul_f32_e32 v99, v99, v205
	v_add_f32_e32 v100, v100, v176
	v_add_f32_e32 v101, v101, v177
	v_add_f32_e32 v102, v102, v178
	v_add_f32_e32 v103, v103, v179
	v_add_f32_e32 v96, v96, v180
	v_add_f32_e32 v97, v97, v181
	v_add_f32_e32 v98, v98, v182
	v_add_f32_e32 v99, v99, v183
	v_mul_f32_e32 v100, 0xbfb8aa3b, v100
	v_mul_f32_e32 v101, 0xbfb8aa3b, v101
	v_mul_f32_e32 v102, 0xbfb8aa3b, v102
	v_mul_f32_e32 v103, 0xbfb8aa3b, v103
	v_mul_f32_e32 v96, 0xbfb8aa3b, v96
	v_mul_f32_e32 v97, 0xbfb8aa3b, v97
	v_mul_f32_e32 v98, 0xbfb8aa3b, v98
	v_mul_f32_e32 v99, 0xbfb8aa3b, v99
	v_exp_f32_e32 v100, v100
	v_exp_f32_e32 v101, v101
	v_exp_f32_e32 v102, v102
	v_exp_f32_e32 v103, v103
	v_exp_f32_e32 v96, v96
	v_exp_f32_e32 v97, v97
	v_exp_f32_e32 v98, v98
	v_exp_f32_e32 v99, v99
	v_add_f32_e32 v100, 1.0, v100
	v_add_f32_e32 v101, 1.0, v101
	v_add_f32_e32 v102, 1.0, v102
	v_add_f32_e32 v103, 1.0, v103
	v_add_f32_e32 v96, 1.0, v96
	v_add_f32_e32 v97, 1.0, v97
	v_add_f32_e32 v98, 1.0, v98
	v_add_f32_e32 v99, 1.0, v99
	v_rcp_f32_e32 v100, v100
	v_rcp_f32_e32 v101, v101
	v_rcp_f32_e32 v102, v102
	v_rcp_f32_e32 v103, v103
	v_rcp_f32_e32 v96, v96
	v_rcp_f32_e32 v97, v97
	v_rcp_f32_e32 v98, v98
	v_rcp_f32_e32 v99, v99
	s_nop 0
	v_cvt_pk_bf16_f32 v100, v100, v101
	v_cvt_pk_bf16_f32 v101, v102, v103
	v_cvt_pk_bf16_f32 v102, v96, v97
	v_cvt_pk_bf16_f32 v103, v98, v99
	s_nop 1
	v_permlane16_swap_b32_e32 v100, v102
	v_permlane16_swap_b32_e32 v101, v103
	global_store_dwordx4 v[198:199], v[100:103], off offset:256
	s_nop 0
	s_mov_b32 s12, 0x80000
	v_lshl_add_u64 v[198:199], v[196:197], 0, s[12:13]
	v_mul_f32_e32 v92, v92, v206
	v_mul_f32_e32 v93, v93, v206
	v_mul_f32_e32 v94, v94, v206
	v_mul_f32_e32 v95, v95, v206
	v_mul_f32_e32 v88, v88, v206
	v_mul_f32_e32 v89, v89, v206
	v_mul_f32_e32 v90, v90, v206
	v_mul_f32_e32 v91, v91, v206
	v_add_f32_e32 v92, v92, v168
	v_add_f32_e32 v93, v93, v169
	v_add_f32_e32 v94, v94, v170
	v_add_f32_e32 v95, v95, v171
	v_add_f32_e32 v88, v88, v172
	v_add_f32_e32 v89, v89, v173
	v_add_f32_e32 v90, v90, v174
	v_add_f32_e32 v91, v91, v175
	v_mul_f32_e32 v92, 0xbfb8aa3b, v92
	v_mul_f32_e32 v93, 0xbfb8aa3b, v93
	v_mul_f32_e32 v94, 0xbfb8aa3b, v94
	v_mul_f32_e32 v95, 0xbfb8aa3b, v95
	v_mul_f32_e32 v88, 0xbfb8aa3b, v88
	v_mul_f32_e32 v89, 0xbfb8aa3b, v89
	v_mul_f32_e32 v90, 0xbfb8aa3b, v90
	v_mul_f32_e32 v91, 0xbfb8aa3b, v91
	v_exp_f32_e32 v92, v92
	v_exp_f32_e32 v93, v93
	v_exp_f32_e32 v94, v94
	v_exp_f32_e32 v95, v95
	v_exp_f32_e32 v88, v88
	v_exp_f32_e32 v89, v89
	v_exp_f32_e32 v90, v90
	v_exp_f32_e32 v91, v91
	v_add_f32_e32 v92, 1.0, v92
	v_add_f32_e32 v93, 1.0, v93
	v_add_f32_e32 v94, 1.0, v94
	v_add_f32_e32 v95, 1.0, v95
	v_add_f32_e32 v88, 1.0, v88
	v_add_f32_e32 v89, 1.0, v89
	v_add_f32_e32 v90, 1.0, v90
	v_add_f32_e32 v91, 1.0, v91
	v_rcp_f32_e32 v92, v92
	v_rcp_f32_e32 v93, v93
	v_rcp_f32_e32 v94, v94
	v_rcp_f32_e32 v95, v95
	v_rcp_f32_e32 v88, v88
	v_rcp_f32_e32 v89, v89
	v_rcp_f32_e32 v90, v90
	v_rcp_f32_e32 v91, v91
	s_nop 0
	v_cvt_pk_bf16_f32 v92, v92, v93
	v_cvt_pk_bf16_f32 v93, v94, v95
	v_cvt_pk_bf16_f32 v94, v88, v89
	v_cvt_pk_bf16_f32 v95, v90, v91
	s_nop 1
	v_permlane16_swap_b32_e32 v92, v94
	v_permlane16_swap_b32_e32 v93, v95
	global_store_dwordx4 v[198:199], v[92:95], off
	v_mul_f32_e32 v84, v84, v206
	v_mul_f32_e32 v85, v85, v206
	v_mul_f32_e32 v86, v86, v206
	v_mul_f32_e32 v87, v87, v206
	v_mul_f32_e32 v80, v80, v206
	v_mul_f32_e32 v81, v81, v206
	v_mul_f32_e32 v82, v82, v206
	v_mul_f32_e32 v83, v83, v206
	v_add_f32_e32 v84, v84, v176
	v_add_f32_e32 v85, v85, v177
	v_add_f32_e32 v86, v86, v178
	v_add_f32_e32 v87, v87, v179
	v_add_f32_e32 v80, v80, v180
	v_add_f32_e32 v81, v81, v181
	v_add_f32_e32 v82, v82, v182
	v_add_f32_e32 v83, v83, v183
	v_mul_f32_e32 v84, 0xbfb8aa3b, v84
	v_mul_f32_e32 v85, 0xbfb8aa3b, v85
	v_mul_f32_e32 v86, 0xbfb8aa3b, v86
	v_mul_f32_e32 v87, 0xbfb8aa3b, v87
	v_mul_f32_e32 v80, 0xbfb8aa3b, v80
	v_mul_f32_e32 v81, 0xbfb8aa3b, v81
	v_mul_f32_e32 v82, 0xbfb8aa3b, v82
	v_mul_f32_e32 v83, 0xbfb8aa3b, v83
	v_exp_f32_e32 v84, v84
	v_exp_f32_e32 v85, v85
	v_exp_f32_e32 v86, v86
	v_exp_f32_e32 v87, v87
	v_exp_f32_e32 v80, v80
	v_exp_f32_e32 v81, v81
	v_exp_f32_e32 v82, v82
	v_exp_f32_e32 v83, v83
	v_add_f32_e32 v84, 1.0, v84
	v_add_f32_e32 v85, 1.0, v85
	v_add_f32_e32 v86, 1.0, v86
	v_add_f32_e32 v87, 1.0, v87
	v_add_f32_e32 v80, 1.0, v80
	v_add_f32_e32 v81, 1.0, v81
	v_add_f32_e32 v82, 1.0, v82
	v_add_f32_e32 v83, 1.0, v83
	v_rcp_f32_e32 v84, v84
	v_rcp_f32_e32 v85, v85
	v_rcp_f32_e32 v86, v86
	v_rcp_f32_e32 v87, v87
	v_rcp_f32_e32 v80, v80
	v_rcp_f32_e32 v81, v81
	v_rcp_f32_e32 v82, v82
	v_rcp_f32_e32 v83, v83
	s_nop 0
	v_cvt_pk_bf16_f32 v84, v84, v85
	v_cvt_pk_bf16_f32 v85, v86, v87
	v_cvt_pk_bf16_f32 v86, v80, v81
	v_cvt_pk_bf16_f32 v87, v82, v83
	s_nop 1
	v_permlane16_swap_b32_e32 v84, v86
	v_permlane16_swap_b32_e32 v85, v87
	global_store_dwordx4 v[198:199], v[84:87], off offset:256
	s_nop 0
	s_mov_b32 s12, 0x90000
	v_lshl_add_u64 v[198:199], v[196:197], 0, s[12:13]
	v_mul_f32_e32 v76, v76, v207
	v_mul_f32_e32 v77, v77, v207
	v_mul_f32_e32 v78, v78, v207
	v_mul_f32_e32 v79, v79, v207
	v_mul_f32_e32 v72, v72, v207
	v_mul_f32_e32 v73, v73, v207
	v_mul_f32_e32 v74, v74, v207
	v_mul_f32_e32 v75, v75, v207
	v_add_f32_e32 v76, v76, v168
	v_add_f32_e32 v77, v77, v169
	v_add_f32_e32 v78, v78, v170
	v_add_f32_e32 v79, v79, v171
	v_add_f32_e32 v72, v72, v172
	v_add_f32_e32 v73, v73, v173
	v_add_f32_e32 v74, v74, v174
	v_add_f32_e32 v75, v75, v175
	v_mul_f32_e32 v76, 0xbfb8aa3b, v76
	v_mul_f32_e32 v77, 0xbfb8aa3b, v77
	v_mul_f32_e32 v78, 0xbfb8aa3b, v78
	v_mul_f32_e32 v79, 0xbfb8aa3b, v79
	v_mul_f32_e32 v72, 0xbfb8aa3b, v72
	v_mul_f32_e32 v73, 0xbfb8aa3b, v73
	v_mul_f32_e32 v74, 0xbfb8aa3b, v74
	v_mul_f32_e32 v75, 0xbfb8aa3b, v75
	v_exp_f32_e32 v76, v76
	v_exp_f32_e32 v77, v77
	v_exp_f32_e32 v78, v78
	v_exp_f32_e32 v79, v79
	v_exp_f32_e32 v72, v72
	v_exp_f32_e32 v73, v73
	v_exp_f32_e32 v74, v74
	v_exp_f32_e32 v75, v75
	v_add_f32_e32 v76, 1.0, v76
	v_add_f32_e32 v77, 1.0, v77
	v_add_f32_e32 v78, 1.0, v78
	v_add_f32_e32 v79, 1.0, v79
	v_add_f32_e32 v72, 1.0, v72
	v_add_f32_e32 v73, 1.0, v73
	v_add_f32_e32 v74, 1.0, v74
	v_add_f32_e32 v75, 1.0, v75
	v_rcp_f32_e32 v76, v76
	v_rcp_f32_e32 v77, v77
	v_rcp_f32_e32 v78, v78
	v_rcp_f32_e32 v79, v79
	v_rcp_f32_e32 v72, v72
	v_rcp_f32_e32 v73, v73
	v_rcp_f32_e32 v74, v74
	v_rcp_f32_e32 v75, v75
	s_nop 0
	v_cvt_pk_bf16_f32 v76, v76, v77
	v_cvt_pk_bf16_f32 v77, v78, v79
	v_cvt_pk_bf16_f32 v78, v72, v73
	v_cvt_pk_bf16_f32 v79, v74, v75
	s_nop 1
	v_permlane16_swap_b32_e32 v76, v78
	v_permlane16_swap_b32_e32 v77, v79
	global_store_dwordx4 v[198:199], v[76:79], off
	v_mul_f32_e32 v68, v68, v207
	v_mul_f32_e32 v69, v69, v207
	v_mul_f32_e32 v70, v70, v207
	v_mul_f32_e32 v71, v71, v207
	v_mul_f32_e32 v64, v64, v207
	v_mul_f32_e32 v65, v65, v207
	v_mul_f32_e32 v66, v66, v207
	v_mul_f32_e32 v67, v67, v207
	v_add_f32_e32 v68, v68, v176
	v_add_f32_e32 v69, v69, v177
	v_add_f32_e32 v70, v70, v178
	v_add_f32_e32 v71, v71, v179
	v_add_f32_e32 v64, v64, v180
	v_add_f32_e32 v65, v65, v181
	v_add_f32_e32 v66, v66, v182
	v_add_f32_e32 v67, v67, v183
	v_mul_f32_e32 v68, 0xbfb8aa3b, v68
	v_mul_f32_e32 v69, 0xbfb8aa3b, v69
	v_mul_f32_e32 v70, 0xbfb8aa3b, v70
	v_mul_f32_e32 v71, 0xbfb8aa3b, v71
	v_mul_f32_e32 v64, 0xbfb8aa3b, v64
	v_mul_f32_e32 v65, 0xbfb8aa3b, v65
	v_mul_f32_e32 v66, 0xbfb8aa3b, v66
	v_mul_f32_e32 v67, 0xbfb8aa3b, v67
	v_exp_f32_e32 v68, v68
	v_exp_f32_e32 v69, v69
	v_exp_f32_e32 v70, v70
	v_exp_f32_e32 v71, v71
	v_exp_f32_e32 v64, v64
	v_exp_f32_e32 v65, v65
	v_exp_f32_e32 v66, v66
	v_exp_f32_e32 v67, v67
	v_add_f32_e32 v68, 1.0, v68
	v_add_f32_e32 v69, 1.0, v69
	v_add_f32_e32 v70, 1.0, v70
	v_add_f32_e32 v71, 1.0, v71
	v_add_f32_e32 v64, 1.0, v64
	v_add_f32_e32 v65, 1.0, v65
	v_add_f32_e32 v66, 1.0, v66
	v_add_f32_e32 v67, 1.0, v67
	v_rcp_f32_e32 v68, v68
	v_rcp_f32_e32 v69, v69
	v_rcp_f32_e32 v70, v70
	v_rcp_f32_e32 v71, v71
	v_rcp_f32_e32 v64, v64
	v_rcp_f32_e32 v65, v65
	v_rcp_f32_e32 v66, v66
	v_rcp_f32_e32 v67, v67
	s_nop 0
	v_cvt_pk_bf16_f32 v68, v68, v69
	v_cvt_pk_bf16_f32 v69, v70, v71
	v_cvt_pk_bf16_f32 v70, v64, v65
	v_cvt_pk_bf16_f32 v71, v66, v67
	s_nop 1
	v_permlane16_swap_b32_e32 v68, v70
	v_permlane16_swap_b32_e32 v69, v71
	global_store_dwordx4 v[198:199], v[68:71], off offset:256
	s_nop 0
	s_mov_b32 s12, 0xa0000
	v_lshl_add_u64 v[198:199], v[196:197], 0, s[12:13]
	v_mul_f32_e32 v60, v60, v208
	v_mul_f32_e32 v61, v61, v208
	v_mul_f32_e32 v62, v62, v208
	v_mul_f32_e32 v63, v63, v208
	v_mul_f32_e32 v56, v56, v208
	v_mul_f32_e32 v57, v57, v208
	v_mul_f32_e32 v58, v58, v208
	v_mul_f32_e32 v59, v59, v208
	v_add_f32_e32 v60, v60, v168
	v_add_f32_e32 v61, v61, v169
	v_add_f32_e32 v62, v62, v170
	v_add_f32_e32 v63, v63, v171
	v_add_f32_e32 v56, v56, v172
	v_add_f32_e32 v57, v57, v173
	v_add_f32_e32 v58, v58, v174
	v_add_f32_e32 v59, v59, v175
	v_mul_f32_e32 v60, 0xbfb8aa3b, v60
	v_mul_f32_e32 v61, 0xbfb8aa3b, v61
	v_mul_f32_e32 v62, 0xbfb8aa3b, v62
	v_mul_f32_e32 v63, 0xbfb8aa3b, v63
	v_mul_f32_e32 v56, 0xbfb8aa3b, v56
	v_mul_f32_e32 v57, 0xbfb8aa3b, v57
	v_mul_f32_e32 v58, 0xbfb8aa3b, v58
	v_mul_f32_e32 v59, 0xbfb8aa3b, v59
	v_exp_f32_e32 v60, v60
	v_exp_f32_e32 v61, v61
	v_exp_f32_e32 v62, v62
	v_exp_f32_e32 v63, v63
	v_exp_f32_e32 v56, v56
	v_exp_f32_e32 v57, v57
	v_exp_f32_e32 v58, v58
	v_exp_f32_e32 v59, v59
	v_add_f32_e32 v60, 1.0, v60
	v_add_f32_e32 v61, 1.0, v61
	v_add_f32_e32 v62, 1.0, v62
	v_add_f32_e32 v63, 1.0, v63
	v_add_f32_e32 v56, 1.0, v56
	v_add_f32_e32 v57, 1.0, v57
	v_add_f32_e32 v58, 1.0, v58
	v_add_f32_e32 v59, 1.0, v59
	v_rcp_f32_e32 v60, v60
	v_rcp_f32_e32 v61, v61
	v_rcp_f32_e32 v62, v62
	v_rcp_f32_e32 v63, v63
	v_rcp_f32_e32 v56, v56
	v_rcp_f32_e32 v57, v57
	v_rcp_f32_e32 v58, v58
	v_rcp_f32_e32 v59, v59
	s_nop 0
	v_cvt_pk_bf16_f32 v60, v60, v61
	v_cvt_pk_bf16_f32 v61, v62, v63
	v_cvt_pk_bf16_f32 v62, v56, v57
	v_cvt_pk_bf16_f32 v63, v58, v59
	s_nop 1
	v_permlane16_swap_b32_e32 v60, v62
	v_permlane16_swap_b32_e32 v61, v63
	global_store_dwordx4 v[198:199], v[60:63], off
	v_mul_f32_e32 v52, v52, v208
	v_mul_f32_e32 v53, v53, v208
	v_mul_f32_e32 v54, v54, v208
	v_mul_f32_e32 v55, v55, v208
	v_mul_f32_e32 v48, v48, v208
	v_mul_f32_e32 v49, v49, v208
	v_mul_f32_e32 v50, v50, v208
	v_mul_f32_e32 v51, v51, v208
	v_add_f32_e32 v52, v52, v176
	v_add_f32_e32 v53, v53, v177
	v_add_f32_e32 v54, v54, v178
	v_add_f32_e32 v55, v55, v179
	v_add_f32_e32 v48, v48, v180
	v_add_f32_e32 v49, v49, v181
	v_add_f32_e32 v50, v50, v182
	v_add_f32_e32 v51, v51, v183
	v_mul_f32_e32 v52, 0xbfb8aa3b, v52
	v_mul_f32_e32 v53, 0xbfb8aa3b, v53
	v_mul_f32_e32 v54, 0xbfb8aa3b, v54
	v_mul_f32_e32 v55, 0xbfb8aa3b, v55
	v_mul_f32_e32 v48, 0xbfb8aa3b, v48
	v_mul_f32_e32 v49, 0xbfb8aa3b, v49
	v_mul_f32_e32 v50, 0xbfb8aa3b, v50
	v_mul_f32_e32 v51, 0xbfb8aa3b, v51
	v_exp_f32_e32 v52, v52
	v_exp_f32_e32 v53, v53
	v_exp_f32_e32 v54, v54
	v_exp_f32_e32 v55, v55
	v_exp_f32_e32 v48, v48
	v_exp_f32_e32 v49, v49
	v_exp_f32_e32 v50, v50
	v_exp_f32_e32 v51, v51
	v_add_f32_e32 v52, 1.0, v52
	v_add_f32_e32 v53, 1.0, v53
	v_add_f32_e32 v54, 1.0, v54
	v_add_f32_e32 v55, 1.0, v55
	v_add_f32_e32 v48, 1.0, v48
	v_add_f32_e32 v49, 1.0, v49
	v_add_f32_e32 v50, 1.0, v50
	v_add_f32_e32 v51, 1.0, v51
	v_rcp_f32_e32 v52, v52
	v_rcp_f32_e32 v53, v53
	v_rcp_f32_e32 v54, v54
	v_rcp_f32_e32 v55, v55
	v_rcp_f32_e32 v48, v48
	v_rcp_f32_e32 v49, v49
	v_rcp_f32_e32 v50, v50
	v_rcp_f32_e32 v51, v51
	s_nop 0
	v_cvt_pk_bf16_f32 v52, v52, v53
	v_cvt_pk_bf16_f32 v53, v54, v55
	v_cvt_pk_bf16_f32 v54, v48, v49
	v_cvt_pk_bf16_f32 v55, v50, v51
	s_nop 1
	v_permlane16_swap_b32_e32 v52, v54
	v_permlane16_swap_b32_e32 v53, v55
	global_store_dwordx4 v[198:199], v[52:55], off offset:256
	s_nop 0
	s_mov_b32 s12, 0xb0000
	v_lshl_add_u64 v[198:199], v[196:197], 0, s[12:13]
	v_mul_f32_e32 v12, v12, v209
	v_mul_f32_e32 v13, v13, v209
	v_mul_f32_e32 v14, v14, v209
	v_mul_f32_e32 v15, v15, v209
	v_mul_f32_e32 v8, v8, v209
	v_mul_f32_e32 v9, v9, v209
	v_mul_f32_e32 v10, v10, v209
	v_mul_f32_e32 v11, v11, v209
	v_add_f32_e32 v12, v12, v168
	v_add_f32_e32 v13, v13, v169
	v_add_f32_e32 v14, v14, v170
	v_add_f32_e32 v15, v15, v171
	v_add_f32_e32 v8, v8, v172
	v_add_f32_e32 v9, v9, v173
	v_add_f32_e32 v10, v10, v174
	v_add_f32_e32 v11, v11, v175
	v_mul_f32_e32 v12, 0xbfb8aa3b, v12
	v_mul_f32_e32 v13, 0xbfb8aa3b, v13
	v_mul_f32_e32 v14, 0xbfb8aa3b, v14
	v_mul_f32_e32 v15, 0xbfb8aa3b, v15
	v_mul_f32_e32 v8, 0xbfb8aa3b, v8
	v_mul_f32_e32 v9, 0xbfb8aa3b, v9
	v_mul_f32_e32 v10, 0xbfb8aa3b, v10
	v_mul_f32_e32 v11, 0xbfb8aa3b, v11
	v_exp_f32_e32 v12, v12
	v_exp_f32_e32 v13, v13
	v_exp_f32_e32 v14, v14
	v_exp_f32_e32 v15, v15
	v_exp_f32_e32 v8, v8
	v_exp_f32_e32 v9, v9
	v_exp_f32_e32 v10, v10
	v_exp_f32_e32 v11, v11
	v_add_f32_e32 v12, 1.0, v12
	v_add_f32_e32 v13, 1.0, v13
	v_add_f32_e32 v14, 1.0, v14
	v_add_f32_e32 v15, 1.0, v15
	v_add_f32_e32 v8, 1.0, v8
	v_add_f32_e32 v9, 1.0, v9
	v_add_f32_e32 v10, 1.0, v10
	v_add_f32_e32 v11, 1.0, v11
	v_rcp_f32_e32 v12, v12
	v_rcp_f32_e32 v13, v13
	v_rcp_f32_e32 v14, v14
	v_rcp_f32_e32 v15, v15
	v_rcp_f32_e32 v8, v8
	v_rcp_f32_e32 v9, v9
	v_rcp_f32_e32 v10, v10
	v_rcp_f32_e32 v11, v11
	s_nop 0
	v_cvt_pk_bf16_f32 v12, v12, v13
	v_cvt_pk_bf16_f32 v13, v14, v15
	v_cvt_pk_bf16_f32 v14, v8, v9
	v_cvt_pk_bf16_f32 v15, v10, v11
	s_nop 1
	v_permlane16_swap_b32_e32 v12, v14
	v_permlane16_swap_b32_e32 v13, v15
	global_store_dwordx4 v[198:199], v[12:15], off
	v_mul_f32_e32 v4, v4, v209
	v_mul_f32_e32 v5, v5, v209
	v_mul_f32_e32 v6, v6, v209
	v_mul_f32_e32 v7, v7, v209
	v_mul_f32_e32 v0, v0, v209
	v_mul_f32_e32 v1, v1, v209
	v_mul_f32_e32 v2, v2, v209
	v_mul_f32_e32 v3, v3, v209
	v_add_f32_e32 v4, v4, v176
	v_add_f32_e32 v5, v5, v177
	v_add_f32_e32 v6, v6, v178
	v_add_f32_e32 v7, v7, v179
	v_add_f32_e32 v0, v0, v180
	v_add_f32_e32 v1, v1, v181
	v_add_f32_e32 v2, v2, v182
	v_add_f32_e32 v3, v3, v183
	v_mul_f32_e32 v4, 0xbfb8aa3b, v4
	v_mul_f32_e32 v5, 0xbfb8aa3b, v5
	v_mul_f32_e32 v6, 0xbfb8aa3b, v6
	v_mul_f32_e32 v7, 0xbfb8aa3b, v7
	v_mul_f32_e32 v0, 0xbfb8aa3b, v0
	v_mul_f32_e32 v1, 0xbfb8aa3b, v1
	v_mul_f32_e32 v2, 0xbfb8aa3b, v2
	v_mul_f32_e32 v3, 0xbfb8aa3b, v3
	v_exp_f32_e32 v4, v4
	v_exp_f32_e32 v5, v5
	v_exp_f32_e32 v6, v6
	v_exp_f32_e32 v7, v7
	v_exp_f32_e32 v0, v0
	v_exp_f32_e32 v1, v1
	v_exp_f32_e32 v2, v2
	v_exp_f32_e32 v3, v3
	v_add_f32_e32 v4, 1.0, v4
	v_add_f32_e32 v5, 1.0, v5
	v_add_f32_e32 v6, 1.0, v6
	v_add_f32_e32 v7, 1.0, v7
	v_add_f32_e32 v0, 1.0, v0
	v_add_f32_e32 v1, 1.0, v1
	v_add_f32_e32 v2, 1.0, v2
	v_add_f32_e32 v3, 1.0, v3
	v_rcp_f32_e32 v4, v4
	v_rcp_f32_e32 v5, v5
	v_rcp_f32_e32 v6, v6
	v_rcp_f32_e32 v7, v7
	v_rcp_f32_e32 v0, v0
	v_rcp_f32_e32 v1, v1
	v_rcp_f32_e32 v2, v2
	v_rcp_f32_e32 v3, v3
	s_nop 0
	v_cvt_pk_bf16_f32 v4, v4, v5
	v_cvt_pk_bf16_f32 v5, v6, v7
	v_cvt_pk_bf16_f32 v6, v0, v1
	v_cvt_pk_bf16_f32 v7, v2, v3
	s_nop 1
	v_permlane16_swap_b32_e32 v4, v6
	v_permlane16_swap_b32_e32 v5, v7
	global_store_dwordx4 v[198:199], v[4:7], off offset:256
	s_branch .LBB0_431
.Lp1f_silu:
	s_lshl_b32 s12, s64, 8
	s_add_i32 s12, s12, s94
	v_add_u32_e32 v196, s12, v186
	v_lshlrev_b32_e32 v196, 10, v196
	s_add_i32 s12, s55, -7
	s_lshl_b32 s12, s12, 8
	s_add_i32 s12, s12, s24
	s_lshl_b32 s12, s12, 1
	v_and_b32_e32 v197, 1, v187
	v_lshlrev_b32_e32 v198, 3, v187
	v_mad_u32_u24 v197, v197, 24, v198
	v_add3_u32 v196, v196, v197, s12
	v_mov_b32_e32 v197, 0
	v_lshl_add_u64 v[196:197], v[196:197], 0, s[20:21]
	s_mov_b32 s13, 0
	s_waitcnt lgkmcnt(0)
	s_mov_b32 s12, 0x0
	v_lshl_add_u64 v[198:199], v[196:197], 0, s[12:13]
	v_mul_f32_e32 v148, v148, v202
	v_mul_f32_e32 v149, v149, v202
	v_mul_f32_e32 v150, v150, v202
	v_mul_f32_e32 v151, v151, v202
	v_mul_f32_e32 v156, v156, v202
	v_mul_f32_e32 v157, v157, v202
	v_mul_f32_e32 v158, v158, v202
	v_mul_f32_e32 v159, v159, v202
	v_mul_f32_e32 v176, 0xbfb8aa3b, v148
	v_mul_f32_e32 v177, 0xbfb8aa3b, v149
	v_mul_f32_e32 v178, 0xbfb8aa3b, v150
	v_mul_f32_e32 v179, 0xbfb8aa3b, v151
	v_mul_f32_e32 v180, 0xbfb8aa3b, v156
	v_mul_f32_e32 v181, 0xbfb8aa3b, v157
	v_mul_f32_e32 v182, 0xbfb8aa3b, v158
	v_mul_f32_e32 v183, 0xbfb8aa3b, v159
	v_exp_f32_e32 v176, v176
	v_exp_f32_e32 v177, v177
	v_exp_f32_e32 v178, v178
	v_exp_f32_e32 v179, v179
	v_exp_f32_e32 v180, v180
	v_exp_f32_e32 v181, v181
	v_exp_f32_e32 v182, v182
	v_exp_f32_e32 v183, v183
	v_add_f32_e32 v176, 1.0, v176
	v_add_f32_e32 v177, 1.0, v177
	v_add_f32_e32 v178, 1.0, v178
	v_add_f32_e32 v179, 1.0, v179
	v_add_f32_e32 v180, 1.0, v180
	v_add_f32_e32 v181, 1.0, v181
	v_add_f32_e32 v182, 1.0, v182
	v_add_f32_e32 v183, 1.0, v183
	v_rcp_f32_e32 v176, v176
	v_rcp_f32_e32 v177, v177
	v_rcp_f32_e32 v178, v178
	v_rcp_f32_e32 v179, v179
	v_rcp_f32_e32 v180, v180
	v_rcp_f32_e32 v181, v181
	v_rcp_f32_e32 v182, v182
	v_rcp_f32_e32 v183, v183
	s_nop 0
	v_mul_f32_e32 v148, v148, v176
	v_mul_f32_e32 v149, v149, v177
	v_mul_f32_e32 v150, v150, v178
	v_mul_f32_e32 v151, v151, v179
	v_mul_f32_e32 v156, v156, v180
	v_mul_f32_e32 v157, v157, v181
	v_mul_f32_e32 v158, v158, v182
	v_mul_f32_e32 v159, v159, v183
	v_cvt_pk_bf16_f32 v148, v148, v149
	v_cvt_pk_bf16_f32 v149, v150, v151
	v_cvt_pk_bf16_f32 v150, v156, v157
	v_cvt_pk_bf16_f32 v151, v158, v159
	s_nop 1
	v_permlane16_swap_b32_e32 v148, v150
	v_permlane16_swap_b32_e32 v149, v151
	global_store_dwordx4 v[198:199], v[148:151], off
	v_mul_f32_e32 v144, v144, v202
	v_mul_f32_e32 v145, v145, v202
	v_mul_f32_e32 v146, v146, v202
	v_mul_f32_e32 v147, v147, v202
	v_mul_f32_e32 v152, v152, v202
	v_mul_f32_e32 v153, v153, v202
	v_mul_f32_e32 v154, v154, v202
	v_mul_f32_e32 v155, v155, v202
	v_mul_f32_e32 v176, 0xbfb8aa3b, v144
	v_mul_f32_e32 v177, 0xbfb8aa3b, v145
	v_mul_f32_e32 v178, 0xbfb8aa3b, v146
	v_mul_f32_e32 v179, 0xbfb8aa3b, v147
	v_mul_f32_e32 v180, 0xbfb8aa3b, v152
	v_mul_f32_e32 v181, 0xbfb8aa3b, v153
	v_mul_f32_e32 v182, 0xbfb8aa3b, v154
	v_mul_f32_e32 v183, 0xbfb8aa3b, v155
	v_exp_f32_e32 v176, v176
	v_exp_f32_e32 v177, v177
	v_exp_f32_e32 v178, v178
	v_exp_f32_e32 v179, v179
	v_exp_f32_e32 v180, v180
	v_exp_f32_e32 v181, v181
	v_exp_f32_e32 v182, v182
	v_exp_f32_e32 v183, v183
	v_add_f32_e32 v176, 1.0, v176
	v_add_f32_e32 v177, 1.0, v177
	v_add_f32_e32 v178, 1.0, v178
	v_add_f32_e32 v179, 1.0, v179
	v_add_f32_e32 v180, 1.0, v180
	v_add_f32_e32 v181, 1.0, v181
	v_add_f32_e32 v182, 1.0, v182
	v_add_f32_e32 v183, 1.0, v183
	v_rcp_f32_e32 v176, v176
	v_rcp_f32_e32 v177, v177
	v_rcp_f32_e32 v178, v178
	v_rcp_f32_e32 v179, v179
	v_rcp_f32_e32 v180, v180
	v_rcp_f32_e32 v181, v181
	v_rcp_f32_e32 v182, v182
	v_rcp_f32_e32 v183, v183
	s_nop 0
	v_mul_f32_e32 v144, v144, v176
	v_mul_f32_e32 v145, v145, v177
	v_mul_f32_e32 v146, v146, v178
	v_mul_f32_e32 v147, v147, v179
	v_mul_f32_e32 v152, v152, v180
	v_mul_f32_e32 v153, v153, v181
	v_mul_f32_e32 v154, v154, v182
	v_mul_f32_e32 v155, v155, v183
	v_cvt_pk_bf16_f32 v144, v144, v145
	v_cvt_pk_bf16_f32 v145, v146, v147
	v_cvt_pk_bf16_f32 v146, v152, v153
	v_cvt_pk_bf16_f32 v147, v154, v155
	s_nop 1
	v_permlane16_swap_b32_e32 v144, v146
	v_permlane16_swap_b32_e32 v145, v147
	global_store_dwordx4 v[198:199], v[144:147], off offset:256
	s_nop 0
	s_mov_b32 s12, 0x4000
	v_lshl_add_u64 v[198:199], v[196:197], 0, s[12:13]
	v_mul_f32_e32 v140, v140, v203
	v_mul_f32_e32 v141, v141, v203
	v_mul_f32_e32 v142, v142, v203
	v_mul_f32_e32 v143, v143, v203
	v_mul_f32_e32 v136, v136, v203
	v_mul_f32_e32 v137, v137, v203
	v_mul_f32_e32 v138, v138, v203
	v_mul_f32_e32 v139, v139, v203
	v_mul_f32_e32 v176, 0xbfb8aa3b, v140
	v_mul_f32_e32 v177, 0xbfb8aa3b, v141
	v_mul_f32_e32 v178, 0xbfb8aa3b, v142
	v_mul_f32_e32 v179, 0xbfb8aa3b, v143
	v_mul_f32_e32 v180, 0xbfb8aa3b, v136
	v_mul_f32_e32 v181, 0xbfb8aa3b, v137
	v_mul_f32_e32 v182, 0xbfb8aa3b, v138
	v_mul_f32_e32 v183, 0xbfb8aa3b, v139
	v_exp_f32_e32 v176, v176
	v_exp_f32_e32 v177, v177
	v_exp_f32_e32 v178, v178
	v_exp_f32_e32 v179, v179
	v_exp_f32_e32 v180, v180
	v_exp_f32_e32 v181, v181
	v_exp_f32_e32 v182, v182
	v_exp_f32_e32 v183, v183
	v_add_f32_e32 v176, 1.0, v176
	v_add_f32_e32 v177, 1.0, v177
	v_add_f32_e32 v178, 1.0, v178
	v_add_f32_e32 v179, 1.0, v179
	v_add_f32_e32 v180, 1.0, v180
	v_add_f32_e32 v181, 1.0, v181
	v_add_f32_e32 v182, 1.0, v182
	v_add_f32_e32 v183, 1.0, v183
	v_rcp_f32_e32 v176, v176
	v_rcp_f32_e32 v177, v177
	v_rcp_f32_e32 v178, v178
	v_rcp_f32_e32 v179, v179
	v_rcp_f32_e32 v180, v180
	v_rcp_f32_e32 v181, v181
	v_rcp_f32_e32 v182, v182
	v_rcp_f32_e32 v183, v183
	s_nop 0
	v_mul_f32_e32 v140, v140, v176
	v_mul_f32_e32 v141, v141, v177
	v_mul_f32_e32 v142, v142, v178
	v_mul_f32_e32 v143, v143, v179
	v_mul_f32_e32 v136, v136, v180
	v_mul_f32_e32 v137, v137, v181
	v_mul_f32_e32 v138, v138, v182
	v_mul_f32_e32 v139, v139, v183
	v_cvt_pk_bf16_f32 v140, v140, v141
	v_cvt_pk_bf16_f32 v141, v142, v143
	v_cvt_pk_bf16_f32 v142, v136, v137
	v_cvt_pk_bf16_f32 v143, v138, v139
	s_nop 1
	v_permlane16_swap_b32_e32 v140, v142
	v_permlane16_swap_b32_e32 v141, v143
	global_store_dwordx4 v[198:199], v[140:143], off
	v_mul_f32_e32 v132, v132, v203
	v_mul_f32_e32 v133, v133, v203
	v_mul_f32_e32 v134, v134, v203
	v_mul_f32_e32 v135, v135, v203
	v_mul_f32_e32 v128, v128, v203
	v_mul_f32_e32 v129, v129, v203
	v_mul_f32_e32 v130, v130, v203
	v_mul_f32_e32 v131, v131, v203
	v_mul_f32_e32 v176, 0xbfb8aa3b, v132
	v_mul_f32_e32 v177, 0xbfb8aa3b, v133
	v_mul_f32_e32 v178, 0xbfb8aa3b, v134
	v_mul_f32_e32 v179, 0xbfb8aa3b, v135
	v_mul_f32_e32 v180, 0xbfb8aa3b, v128
	v_mul_f32_e32 v181, 0xbfb8aa3b, v129
	v_mul_f32_e32 v182, 0xbfb8aa3b, v130
	v_mul_f32_e32 v183, 0xbfb8aa3b, v131
	v_exp_f32_e32 v176, v176
	v_exp_f32_e32 v177, v177
	v_exp_f32_e32 v178, v178
	v_exp_f32_e32 v179, v179
	v_exp_f32_e32 v180, v180
	v_exp_f32_e32 v181, v181
	v_exp_f32_e32 v182, v182
	v_exp_f32_e32 v183, v183
	v_add_f32_e32 v176, 1.0, v176
	v_add_f32_e32 v177, 1.0, v177
	v_add_f32_e32 v178, 1.0, v178
	v_add_f32_e32 v179, 1.0, v179
	v_add_f32_e32 v180, 1.0, v180
	v_add_f32_e32 v181, 1.0, v181
	v_add_f32_e32 v182, 1.0, v182
	v_add_f32_e32 v183, 1.0, v183
	v_rcp_f32_e32 v176, v176
	v_rcp_f32_e32 v177, v177
	v_rcp_f32_e32 v178, v178
	v_rcp_f32_e32 v179, v179
	v_rcp_f32_e32 v180, v180
	v_rcp_f32_e32 v181, v181
	v_rcp_f32_e32 v182, v182
	v_rcp_f32_e32 v183, v183
	s_nop 0
	v_mul_f32_e32 v132, v132, v176
	v_mul_f32_e32 v133, v133, v177
	v_mul_f32_e32 v134, v134, v178
	v_mul_f32_e32 v135, v135, v179
	v_mul_f32_e32 v128, v128, v180
	v_mul_f32_e32 v129, v129, v181
	v_mul_f32_e32 v130, v130, v182
	v_mul_f32_e32 v131, v131, v183
	v_cvt_pk_bf16_f32 v132, v132, v133
	v_cvt_pk_bf16_f32 v133, v134, v135
	v_cvt_pk_bf16_f32 v134, v128, v129
	v_cvt_pk_bf16_f32 v135, v130, v131
	s_nop 1
	v_permlane16_swap_b32_e32 v132, v134
	v_permlane16_swap_b32_e32 v133, v135
	global_store_dwordx4 v[198:199], v[132:135], off offset:256
	s_nop 0
	s_mov_b32 s12, 0x8000
	v_lshl_add_u64 v[198:199], v[196:197], 0, s[12:13]
	v_mul_f32_e32 v124, v124, v204
	v_mul_f32_e32 v125, v125, v204
	v_mul_f32_e32 v126, v126, v204
	v_mul_f32_e32 v127, v127, v204
	v_mul_f32_e32 v120, v120, v204
	v_mul_f32_e32 v121, v121, v204
	v_mul_f32_e32 v122, v122, v204
	v_mul_f32_e32 v123, v123, v204
	v_mul_f32_e32 v176, 0xbfb8aa3b, v124
	v_mul_f32_e32 v177, 0xbfb8aa3b, v125
	v_mul_f32_e32 v178, 0xbfb8aa3b, v126
	v_mul_f32_e32 v179, 0xbfb8aa3b, v127
	v_mul_f32_e32 v180, 0xbfb8aa3b, v120
	v_mul_f32_e32 v181, 0xbfb8aa3b, v121
	v_mul_f32_e32 v182, 0xbfb8aa3b, v122
	v_mul_f32_e32 v183, 0xbfb8aa3b, v123
	v_exp_f32_e32 v176, v176
	v_exp_f32_e32 v177, v177
	v_exp_f32_e32 v178, v178
	v_exp_f32_e32 v179, v179
	v_exp_f32_e32 v180, v180
	v_exp_f32_e32 v181, v181
	v_exp_f32_e32 v182, v182
	v_exp_f32_e32 v183, v183
	v_add_f32_e32 v176, 1.0, v176
	v_add_f32_e32 v177, 1.0, v177
	v_add_f32_e32 v178, 1.0, v178
	v_add_f32_e32 v179, 1.0, v179
	v_add_f32_e32 v180, 1.0, v180
	v_add_f32_e32 v181, 1.0, v181
	v_add_f32_e32 v182, 1.0, v182
	v_add_f32_e32 v183, 1.0, v183
	v_rcp_f32_e32 v176, v176
	v_rcp_f32_e32 v177, v177
	v_rcp_f32_e32 v178, v178
	v_rcp_f32_e32 v179, v179
	v_rcp_f32_e32 v180, v180
	v_rcp_f32_e32 v181, v181
	v_rcp_f32_e32 v182, v182
	v_rcp_f32_e32 v183, v183
	s_nop 0
	v_mul_f32_e32 v124, v124, v176
	v_mul_f32_e32 v125, v125, v177
	v_mul_f32_e32 v126, v126, v178
	v_mul_f32_e32 v127, v127, v179
	v_mul_f32_e32 v120, v120, v180
	v_mul_f32_e32 v121, v121, v181
	v_mul_f32_e32 v122, v122, v182
	v_mul_f32_e32 v123, v123, v183
	v_cvt_pk_bf16_f32 v124, v124, v125
	v_cvt_pk_bf16_f32 v125, v126, v127
	v_cvt_pk_bf16_f32 v126, v120, v121
	v_cvt_pk_bf16_f32 v127, v122, v123
	s_nop 1
	v_permlane16_swap_b32_e32 v124, v126
	v_permlane16_swap_b32_e32 v125, v127
	global_store_dwordx4 v[198:199], v[124:127], off
	v_mul_f32_e32 v116, v116, v204
	v_mul_f32_e32 v117, v117, v204
	v_mul_f32_e32 v118, v118, v204
	v_mul_f32_e32 v119, v119, v204
	v_mul_f32_e32 v112, v112, v204
	v_mul_f32_e32 v113, v113, v204
	v_mul_f32_e32 v114, v114, v204
	v_mul_f32_e32 v115, v115, v204
	v_mul_f32_e32 v176, 0xbfb8aa3b, v116
	v_mul_f32_e32 v177, 0xbfb8aa3b, v117
	v_mul_f32_e32 v178, 0xbfb8aa3b, v118
	v_mul_f32_e32 v179, 0xbfb8aa3b, v119
	v_mul_f32_e32 v180, 0xbfb8aa3b, v112
	v_mul_f32_e32 v181, 0xbfb8aa3b, v113
	v_mul_f32_e32 v182, 0xbfb8aa3b, v114
	v_mul_f32_e32 v183, 0xbfb8aa3b, v115
	v_exp_f32_e32 v176, v176
	v_exp_f32_e32 v177, v177
	v_exp_f32_e32 v178, v178
	v_exp_f32_e32 v179, v179
	v_exp_f32_e32 v180, v180
	v_exp_f32_e32 v181, v181
	v_exp_f32_e32 v182, v182
	v_exp_f32_e32 v183, v183
	v_add_f32_e32 v176, 1.0, v176
	v_add_f32_e32 v177, 1.0, v177
	v_add_f32_e32 v178, 1.0, v178
	v_add_f32_e32 v179, 1.0, v179
	v_add_f32_e32 v180, 1.0, v180
	v_add_f32_e32 v181, 1.0, v181
	v_add_f32_e32 v182, 1.0, v182
	v_add_f32_e32 v183, 1.0, v183
	v_rcp_f32_e32 v176, v176
	v_rcp_f32_e32 v177, v177
	v_rcp_f32_e32 v178, v178
	v_rcp_f32_e32 v179, v179
	v_rcp_f32_e32 v180, v180
	v_rcp_f32_e32 v181, v181
	v_rcp_f32_e32 v182, v182
	v_rcp_f32_e32 v183, v183
	s_nop 0
	v_mul_f32_e32 v116, v116, v176
	v_mul_f32_e32 v117, v117, v177
	v_mul_f32_e32 v118, v118, v178
	v_mul_f32_e32 v119, v119, v179
	v_mul_f32_e32 v112, v112, v180
	v_mul_f32_e32 v113, v113, v181
	v_mul_f32_e32 v114, v114, v182
	v_mul_f32_e32 v115, v115, v183
	v_cvt_pk_bf16_f32 v116, v116, v117
	v_cvt_pk_bf16_f32 v117, v118, v119
	v_cvt_pk_bf16_f32 v118, v112, v113
	v_cvt_pk_bf16_f32 v119, v114, v115
	s_nop 1
	v_permlane16_swap_b32_e32 v116, v118
	v_permlane16_swap_b32_e32 v117, v119
	global_store_dwordx4 v[198:199], v[116:119], off offset:256
	s_nop 0
	s_mov_b32 s12, 0xc000
	v_lshl_add_u64 v[198:199], v[196:197], 0, s[12:13]
	v_mul_f32_e32 v108, v108, v205
	v_mul_f32_e32 v109, v109, v205
	v_mul_f32_e32 v110, v110, v205
	v_mul_f32_e32 v111, v111, v205
	v_mul_f32_e32 v104, v104, v205
	v_mul_f32_e32 v105, v105, v205
	v_mul_f32_e32 v106, v106, v205
	v_mul_f32_e32 v107, v107, v205
	v_mul_f32_e32 v176, 0xbfb8aa3b, v108
	v_mul_f32_e32 v177, 0xbfb8aa3b, v109
	v_mul_f32_e32 v178, 0xbfb8aa3b, v110
	v_mul_f32_e32 v179, 0xbfb8aa3b, v111
	v_mul_f32_e32 v180, 0xbfb8aa3b, v104
	v_mul_f32_e32 v181, 0xbfb8aa3b, v105
	v_mul_f32_e32 v182, 0xbfb8aa3b, v106
	v_mul_f32_e32 v183, 0xbfb8aa3b, v107
	v_exp_f32_e32 v176, v176
	v_exp_f32_e32 v177, v177
	v_exp_f32_e32 v178, v178
	v_exp_f32_e32 v179, v179
	v_exp_f32_e32 v180, v180
	v_exp_f32_e32 v181, v181
	v_exp_f32_e32 v182, v182
	v_exp_f32_e32 v183, v183
	v_add_f32_e32 v176, 1.0, v176
	v_add_f32_e32 v177, 1.0, v177
	v_add_f32_e32 v178, 1.0, v178
	v_add_f32_e32 v179, 1.0, v179
	v_add_f32_e32 v180, 1.0, v180
	v_add_f32_e32 v181, 1.0, v181
	v_add_f32_e32 v182, 1.0, v182
	v_add_f32_e32 v183, 1.0, v183
	v_rcp_f32_e32 v176, v176
	v_rcp_f32_e32 v177, v177
	v_rcp_f32_e32 v178, v178
	v_rcp_f32_e32 v179, v179
	v_rcp_f32_e32 v180, v180
	v_rcp_f32_e32 v181, v181
	v_rcp_f32_e32 v182, v182
	v_rcp_f32_e32 v183, v183
	s_nop 0
	v_mul_f32_e32 v108, v108, v176
	v_mul_f32_e32 v109, v109, v177
	v_mul_f32_e32 v110, v110, v178
	v_mul_f32_e32 v111, v111, v179
	v_mul_f32_e32 v104, v104, v180
	v_mul_f32_e32 v105, v105, v181
	v_mul_f32_e32 v106, v106, v182
	v_mul_f32_e32 v107, v107, v183
	v_cvt_pk_bf16_f32 v108, v108, v109
	v_cvt_pk_bf16_f32 v109, v110, v111
	v_cvt_pk_bf16_f32 v110, v104, v105
	v_cvt_pk_bf16_f32 v111, v106, v107
	s_nop 1
	v_permlane16_swap_b32_e32 v108, v110
	v_permlane16_swap_b32_e32 v109, v111
	global_store_dwordx4 v[198:199], v[108:111], off
	v_mul_f32_e32 v100, v100, v205
	v_mul_f32_e32 v101, v101, v205
	v_mul_f32_e32 v102, v102, v205
	v_mul_f32_e32 v103, v103, v205
	v_mul_f32_e32 v96, v96, v205
	v_mul_f32_e32 v97, v97, v205
	v_mul_f32_e32 v98, v98, v205
	v_mul_f32_e32 v99, v99, v205
	v_mul_f32_e32 v176, 0xbfb8aa3b, v100
	v_mul_f32_e32 v177, 0xbfb8aa3b, v101
	v_mul_f32_e32 v178, 0xbfb8aa3b, v102
	v_mul_f32_e32 v179, 0xbfb8aa3b, v103
	v_mul_f32_e32 v180, 0xbfb8aa3b, v96
	v_mul_f32_e32 v181, 0xbfb8aa3b, v97
	v_mul_f32_e32 v182, 0xbfb8aa3b, v98
	v_mul_f32_e32 v183, 0xbfb8aa3b, v99
	v_exp_f32_e32 v176, v176
	v_exp_f32_e32 v177, v177
	v_exp_f32_e32 v178, v178
	v_exp_f32_e32 v179, v179
	v_exp_f32_e32 v180, v180
	v_exp_f32_e32 v181, v181
	v_exp_f32_e32 v182, v182
	v_exp_f32_e32 v183, v183
	v_add_f32_e32 v176, 1.0, v176
	v_add_f32_e32 v177, 1.0, v177
	v_add_f32_e32 v178, 1.0, v178
	v_add_f32_e32 v179, 1.0, v179
	v_add_f32_e32 v180, 1.0, v180
	v_add_f32_e32 v181, 1.0, v181
	v_add_f32_e32 v182, 1.0, v182
	v_add_f32_e32 v183, 1.0, v183
	v_rcp_f32_e32 v176, v176
	v_rcp_f32_e32 v177, v177
	v_rcp_f32_e32 v178, v178
	v_rcp_f32_e32 v179, v179
	v_rcp_f32_e32 v180, v180
	v_rcp_f32_e32 v181, v181
	v_rcp_f32_e32 v182, v182
	v_rcp_f32_e32 v183, v183
	s_nop 0
	v_mul_f32_e32 v100, v100, v176
	v_mul_f32_e32 v101, v101, v177
	v_mul_f32_e32 v102, v102, v178
	v_mul_f32_e32 v103, v103, v179
	v_mul_f32_e32 v96, v96, v180
	v_mul_f32_e32 v97, v97, v181
	v_mul_f32_e32 v98, v98, v182
	v_mul_f32_e32 v99, v99, v183
	v_cvt_pk_bf16_f32 v100, v100, v101
	v_cvt_pk_bf16_f32 v101, v102, v103
	v_cvt_pk_bf16_f32 v102, v96, v97
	v_cvt_pk_bf16_f32 v103, v98, v99
	s_nop 1
	v_permlane16_swap_b32_e32 v100, v102
	v_permlane16_swap_b32_e32 v101, v103
	global_store_dwordx4 v[198:199], v[100:103], off offset:256
	s_nop 0
	s_mov_b32 s12, 0x20000
	v_lshl_add_u64 v[198:199], v[196:197], 0, s[12:13]
	v_mul_f32_e32 v92, v92, v206
	v_mul_f32_e32 v93, v93, v206
	v_mul_f32_e32 v94, v94, v206
	v_mul_f32_e32 v95, v95, v206
	v_mul_f32_e32 v88, v88, v206
	v_mul_f32_e32 v89, v89, v206
	v_mul_f32_e32 v90, v90, v206
	v_mul_f32_e32 v91, v91, v206
	v_mul_f32_e32 v176, 0xbfb8aa3b, v92
	v_mul_f32_e32 v177, 0xbfb8aa3b, v93
	v_mul_f32_e32 v178, 0xbfb8aa3b, v94
	v_mul_f32_e32 v179, 0xbfb8aa3b, v95
	v_mul_f32_e32 v180, 0xbfb8aa3b, v88
	v_mul_f32_e32 v181, 0xbfb8aa3b, v89
	v_mul_f32_e32 v182, 0xbfb8aa3b, v90
	v_mul_f32_e32 v183, 0xbfb8aa3b, v91
	v_exp_f32_e32 v176, v176
	v_exp_f32_e32 v177, v177
	v_exp_f32_e32 v178, v178
	v_exp_f32_e32 v179, v179
	v_exp_f32_e32 v180, v180
	v_exp_f32_e32 v181, v181
	v_exp_f32_e32 v182, v182
	v_exp_f32_e32 v183, v183
	v_add_f32_e32 v176, 1.0, v176
	v_add_f32_e32 v177, 1.0, v177
	v_add_f32_e32 v178, 1.0, v178
	v_add_f32_e32 v179, 1.0, v179
	v_add_f32_e32 v180, 1.0, v180
	v_add_f32_e32 v181, 1.0, v181
	v_add_f32_e32 v182, 1.0, v182
	v_add_f32_e32 v183, 1.0, v183
	v_rcp_f32_e32 v176, v176
	v_rcp_f32_e32 v177, v177
	v_rcp_f32_e32 v178, v178
	v_rcp_f32_e32 v179, v179
	v_rcp_f32_e32 v180, v180
	v_rcp_f32_e32 v181, v181
	v_rcp_f32_e32 v182, v182
	v_rcp_f32_e32 v183, v183
	s_nop 0
	v_mul_f32_e32 v92, v92, v176
	v_mul_f32_e32 v93, v93, v177
	v_mul_f32_e32 v94, v94, v178
	v_mul_f32_e32 v95, v95, v179
	v_mul_f32_e32 v88, v88, v180
	v_mul_f32_e32 v89, v89, v181
	v_mul_f32_e32 v90, v90, v182
	v_mul_f32_e32 v91, v91, v183
	v_cvt_pk_bf16_f32 v92, v92, v93
	v_cvt_pk_bf16_f32 v93, v94, v95
	v_cvt_pk_bf16_f32 v94, v88, v89
	v_cvt_pk_bf16_f32 v95, v90, v91
	s_nop 1
	v_permlane16_swap_b32_e32 v92, v94
	v_permlane16_swap_b32_e32 v93, v95
	global_store_dwordx4 v[198:199], v[92:95], off
	v_mul_f32_e32 v84, v84, v206
	v_mul_f32_e32 v85, v85, v206
	v_mul_f32_e32 v86, v86, v206
	v_mul_f32_e32 v87, v87, v206
	v_mul_f32_e32 v80, v80, v206
	v_mul_f32_e32 v81, v81, v206
	v_mul_f32_e32 v82, v82, v206
	v_mul_f32_e32 v83, v83, v206
	v_mul_f32_e32 v176, 0xbfb8aa3b, v84
	v_mul_f32_e32 v177, 0xbfb8aa3b, v85
	v_mul_f32_e32 v178, 0xbfb8aa3b, v86
	v_mul_f32_e32 v179, 0xbfb8aa3b, v87
	v_mul_f32_e32 v180, 0xbfb8aa3b, v80
	v_mul_f32_e32 v181, 0xbfb8aa3b, v81
	v_mul_f32_e32 v182, 0xbfb8aa3b, v82
	v_mul_f32_e32 v183, 0xbfb8aa3b, v83
	v_exp_f32_e32 v176, v176
	v_exp_f32_e32 v177, v177
	v_exp_f32_e32 v178, v178
	v_exp_f32_e32 v179, v179
	v_exp_f32_e32 v180, v180
	v_exp_f32_e32 v181, v181
	v_exp_f32_e32 v182, v182
	v_exp_f32_e32 v183, v183
	v_add_f32_e32 v176, 1.0, v176
	v_add_f32_e32 v177, 1.0, v177
	v_add_f32_e32 v178, 1.0, v178
	v_add_f32_e32 v179, 1.0, v179
	v_add_f32_e32 v180, 1.0, v180
	v_add_f32_e32 v181, 1.0, v181
	v_add_f32_e32 v182, 1.0, v182
	v_add_f32_e32 v183, 1.0, v183
	v_rcp_f32_e32 v176, v176
	v_rcp_f32_e32 v177, v177
	v_rcp_f32_e32 v178, v178
	v_rcp_f32_e32 v179, v179
	v_rcp_f32_e32 v180, v180
	v_rcp_f32_e32 v181, v181
	v_rcp_f32_e32 v182, v182
	v_rcp_f32_e32 v183, v183
	s_nop 0
	v_mul_f32_e32 v84, v84, v176
	v_mul_f32_e32 v85, v85, v177
	v_mul_f32_e32 v86, v86, v178
	v_mul_f32_e32 v87, v87, v179
	v_mul_f32_e32 v80, v80, v180
	v_mul_f32_e32 v81, v81, v181
	v_mul_f32_e32 v82, v82, v182
	v_mul_f32_e32 v83, v83, v183
	v_cvt_pk_bf16_f32 v84, v84, v85
	v_cvt_pk_bf16_f32 v85, v86, v87
	v_cvt_pk_bf16_f32 v86, v80, v81
	v_cvt_pk_bf16_f32 v87, v82, v83
	s_nop 1
	v_permlane16_swap_b32_e32 v84, v86
	v_permlane16_swap_b32_e32 v85, v87
	global_store_dwordx4 v[198:199], v[84:87], off offset:256
	s_nop 0
	s_mov_b32 s12, 0x24000
	v_lshl_add_u64 v[198:199], v[196:197], 0, s[12:13]
	v_mul_f32_e32 v76, v76, v207
	v_mul_f32_e32 v77, v77, v207
	v_mul_f32_e32 v78, v78, v207
	v_mul_f32_e32 v79, v79, v207
	v_mul_f32_e32 v72, v72, v207
	v_mul_f32_e32 v73, v73, v207
	v_mul_f32_e32 v74, v74, v207
	v_mul_f32_e32 v75, v75, v207
	v_mul_f32_e32 v176, 0xbfb8aa3b, v76
	v_mul_f32_e32 v177, 0xbfb8aa3b, v77
	v_mul_f32_e32 v178, 0xbfb8aa3b, v78
	v_mul_f32_e32 v179, 0xbfb8aa3b, v79
	v_mul_f32_e32 v180, 0xbfb8aa3b, v72
	v_mul_f32_e32 v181, 0xbfb8aa3b, v73
	v_mul_f32_e32 v182, 0xbfb8aa3b, v74
	v_mul_f32_e32 v183, 0xbfb8aa3b, v75
	v_exp_f32_e32 v176, v176
	v_exp_f32_e32 v177, v177
	v_exp_f32_e32 v178, v178
	v_exp_f32_e32 v179, v179
	v_exp_f32_e32 v180, v180
	v_exp_f32_e32 v181, v181
	v_exp_f32_e32 v182, v182
	v_exp_f32_e32 v183, v183
	v_add_f32_e32 v176, 1.0, v176
	v_add_f32_e32 v177, 1.0, v177
	v_add_f32_e32 v178, 1.0, v178
	v_add_f32_e32 v179, 1.0, v179
	v_add_f32_e32 v180, 1.0, v180
	v_add_f32_e32 v181, 1.0, v181
	v_add_f32_e32 v182, 1.0, v182
	v_add_f32_e32 v183, 1.0, v183
	v_rcp_f32_e32 v176, v176
	v_rcp_f32_e32 v177, v177
	v_rcp_f32_e32 v178, v178
	v_rcp_f32_e32 v179, v179
	v_rcp_f32_e32 v180, v180
	v_rcp_f32_e32 v181, v181
	v_rcp_f32_e32 v182, v182
	v_rcp_f32_e32 v183, v183
	s_nop 0
	v_mul_f32_e32 v76, v76, v176
	v_mul_f32_e32 v77, v77, v177
	v_mul_f32_e32 v78, v78, v178
	v_mul_f32_e32 v79, v79, v179
	v_mul_f32_e32 v72, v72, v180
	v_mul_f32_e32 v73, v73, v181
	v_mul_f32_e32 v74, v74, v182
	v_mul_f32_e32 v75, v75, v183
	v_cvt_pk_bf16_f32 v76, v76, v77
	v_cvt_pk_bf16_f32 v77, v78, v79
	v_cvt_pk_bf16_f32 v78, v72, v73
	v_cvt_pk_bf16_f32 v79, v74, v75
	s_nop 1
	v_permlane16_swap_b32_e32 v76, v78
	v_permlane16_swap_b32_e32 v77, v79
	global_store_dwordx4 v[198:199], v[76:79], off
	v_mul_f32_e32 v68, v68, v207
	v_mul_f32_e32 v69, v69, v207
	v_mul_f32_e32 v70, v70, v207
	v_mul_f32_e32 v71, v71, v207
	v_mul_f32_e32 v64, v64, v207
	v_mul_f32_e32 v65, v65, v207
	v_mul_f32_e32 v66, v66, v207
	v_mul_f32_e32 v67, v67, v207
	v_mul_f32_e32 v176, 0xbfb8aa3b, v68
	v_mul_f32_e32 v177, 0xbfb8aa3b, v69
	v_mul_f32_e32 v178, 0xbfb8aa3b, v70
	v_mul_f32_e32 v179, 0xbfb8aa3b, v71
	v_mul_f32_e32 v180, 0xbfb8aa3b, v64
	v_mul_f32_e32 v181, 0xbfb8aa3b, v65
	v_mul_f32_e32 v182, 0xbfb8aa3b, v66
	v_mul_f32_e32 v183, 0xbfb8aa3b, v67
	v_exp_f32_e32 v176, v176
	v_exp_f32_e32 v177, v177
	v_exp_f32_e32 v178, v178
	v_exp_f32_e32 v179, v179
	v_exp_f32_e32 v180, v180
	v_exp_f32_e32 v181, v181
	v_exp_f32_e32 v182, v182
	v_exp_f32_e32 v183, v183
	v_add_f32_e32 v176, 1.0, v176
	v_add_f32_e32 v177, 1.0, v177
	v_add_f32_e32 v178, 1.0, v178
	v_add_f32_e32 v179, 1.0, v179
	v_add_f32_e32 v180, 1.0, v180
	v_add_f32_e32 v181, 1.0, v181
	v_add_f32_e32 v182, 1.0, v182
	v_add_f32_e32 v183, 1.0, v183
	v_rcp_f32_e32 v176, v176
	v_rcp_f32_e32 v177, v177
	v_rcp_f32_e32 v178, v178
	v_rcp_f32_e32 v179, v179
	v_rcp_f32_e32 v180, v180
	v_rcp_f32_e32 v181, v181
	v_rcp_f32_e32 v182, v182
	v_rcp_f32_e32 v183, v183
	s_nop 0
	v_mul_f32_e32 v68, v68, v176
	v_mul_f32_e32 v69, v69, v177
	v_mul_f32_e32 v70, v70, v178
	v_mul_f32_e32 v71, v71, v179
	v_mul_f32_e32 v64, v64, v180
	v_mul_f32_e32 v65, v65, v181
	v_mul_f32_e32 v66, v66, v182
	v_mul_f32_e32 v67, v67, v183
	v_cvt_pk_bf16_f32 v68, v68, v69
	v_cvt_pk_bf16_f32 v69, v70, v71
	v_cvt_pk_bf16_f32 v70, v64, v65
	v_cvt_pk_bf16_f32 v71, v66, v67
	s_nop 1
	v_permlane16_swap_b32_e32 v68, v70
	v_permlane16_swap_b32_e32 v69, v71
	global_store_dwordx4 v[198:199], v[68:71], off offset:256
	s_nop 0
	s_mov_b32 s12, 0x28000
	v_lshl_add_u64 v[198:199], v[196:197], 0, s[12:13]
	v_mul_f32_e32 v60, v60, v208
	v_mul_f32_e32 v61, v61, v208
	v_mul_f32_e32 v62, v62, v208
	v_mul_f32_e32 v63, v63, v208
	v_mul_f32_e32 v56, v56, v208
	v_mul_f32_e32 v57, v57, v208
	v_mul_f32_e32 v58, v58, v208
	v_mul_f32_e32 v59, v59, v208
	v_mul_f32_e32 v176, 0xbfb8aa3b, v60
	v_mul_f32_e32 v177, 0xbfb8aa3b, v61
	v_mul_f32_e32 v178, 0xbfb8aa3b, v62
	v_mul_f32_e32 v179, 0xbfb8aa3b, v63
	v_mul_f32_e32 v180, 0xbfb8aa3b, v56
	v_mul_f32_e32 v181, 0xbfb8aa3b, v57
	v_mul_f32_e32 v182, 0xbfb8aa3b, v58
	v_mul_f32_e32 v183, 0xbfb8aa3b, v59
	v_exp_f32_e32 v176, v176
	v_exp_f32_e32 v177, v177
	v_exp_f32_e32 v178, v178
	v_exp_f32_e32 v179, v179
	v_exp_f32_e32 v180, v180
	v_exp_f32_e32 v181, v181
	v_exp_f32_e32 v182, v182
	v_exp_f32_e32 v183, v183
	v_add_f32_e32 v176, 1.0, v176
	v_add_f32_e32 v177, 1.0, v177
	v_add_f32_e32 v178, 1.0, v178
	v_add_f32_e32 v179, 1.0, v179
	v_add_f32_e32 v180, 1.0, v180
	v_add_f32_e32 v181, 1.0, v181
	v_add_f32_e32 v182, 1.0, v182
	v_add_f32_e32 v183, 1.0, v183
	v_rcp_f32_e32 v176, v176
	v_rcp_f32_e32 v177, v177
	v_rcp_f32_e32 v178, v178
	v_rcp_f32_e32 v179, v179
	v_rcp_f32_e32 v180, v180
	v_rcp_f32_e32 v181, v181
	v_rcp_f32_e32 v182, v182
	v_rcp_f32_e32 v183, v183
	s_nop 0
	v_mul_f32_e32 v60, v60, v176
	v_mul_f32_e32 v61, v61, v177
	v_mul_f32_e32 v62, v62, v178
	v_mul_f32_e32 v63, v63, v179
	v_mul_f32_e32 v56, v56, v180
	v_mul_f32_e32 v57, v57, v181
	v_mul_f32_e32 v58, v58, v182
	v_mul_f32_e32 v59, v59, v183
	v_cvt_pk_bf16_f32 v60, v60, v61
	v_cvt_pk_bf16_f32 v61, v62, v63
	v_cvt_pk_bf16_f32 v62, v56, v57
	v_cvt_pk_bf16_f32 v63, v58, v59
	s_nop 1
	v_permlane16_swap_b32_e32 v60, v62
	v_permlane16_swap_b32_e32 v61, v63
	global_store_dwordx4 v[198:199], v[60:63], off
	v_mul_f32_e32 v52, v52, v208
	v_mul_f32_e32 v53, v53, v208
	v_mul_f32_e32 v54, v54, v208
	v_mul_f32_e32 v55, v55, v208
	v_mul_f32_e32 v48, v48, v208
	v_mul_f32_e32 v49, v49, v208
	v_mul_f32_e32 v50, v50, v208
	v_mul_f32_e32 v51, v51, v208
	v_mul_f32_e32 v176, 0xbfb8aa3b, v52
	v_mul_f32_e32 v177, 0xbfb8aa3b, v53
	v_mul_f32_e32 v178, 0xbfb8aa3b, v54
	v_mul_f32_e32 v179, 0xbfb8aa3b, v55
	v_mul_f32_e32 v180, 0xbfb8aa3b, v48
	v_mul_f32_e32 v181, 0xbfb8aa3b, v49
	v_mul_f32_e32 v182, 0xbfb8aa3b, v50
	v_mul_f32_e32 v183, 0xbfb8aa3b, v51
	v_exp_f32_e32 v176, v176
	v_exp_f32_e32 v177, v177
	v_exp_f32_e32 v178, v178
	v_exp_f32_e32 v179, v179
	v_exp_f32_e32 v180, v180
	v_exp_f32_e32 v181, v181
	v_exp_f32_e32 v182, v182
	v_exp_f32_e32 v183, v183
	v_add_f32_e32 v176, 1.0, v176
	v_add_f32_e32 v177, 1.0, v177
	v_add_f32_e32 v178, 1.0, v178
	v_add_f32_e32 v179, 1.0, v179
	v_add_f32_e32 v180, 1.0, v180
	v_add_f32_e32 v181, 1.0, v181
	v_add_f32_e32 v182, 1.0, v182
	v_add_f32_e32 v183, 1.0, v183
	v_rcp_f32_e32 v176, v176
	v_rcp_f32_e32 v177, v177
	v_rcp_f32_e32 v178, v178
	v_rcp_f32_e32 v179, v179
	v_rcp_f32_e32 v180, v180
	v_rcp_f32_e32 v181, v181
	v_rcp_f32_e32 v182, v182
	v_rcp_f32_e32 v183, v183
	s_nop 0
	v_mul_f32_e32 v52, v52, v176
	v_mul_f32_e32 v53, v53, v177
	v_mul_f32_e32 v54, v54, v178
	v_mul_f32_e32 v55, v55, v179
	v_mul_f32_e32 v48, v48, v180
	v_mul_f32_e32 v49, v49, v181
	v_mul_f32_e32 v50, v50, v182
	v_mul_f32_e32 v51, v51, v183
	v_cvt_pk_bf16_f32 v52, v52, v53
	v_cvt_pk_bf16_f32 v53, v54, v55
	v_cvt_pk_bf16_f32 v54, v48, v49
	v_cvt_pk_bf16_f32 v55, v50, v51
	s_nop 1
	v_permlane16_swap_b32_e32 v52, v54
	v_permlane16_swap_b32_e32 v53, v55
	global_store_dwordx4 v[198:199], v[52:55], off offset:256
	s_nop 0
	s_mov_b32 s12, 0x2c000
	v_lshl_add_u64 v[198:199], v[196:197], 0, s[12:13]
	v_mul_f32_e32 v12, v12, v209
	v_mul_f32_e32 v13, v13, v209
	v_mul_f32_e32 v14, v14, v209
	v_mul_f32_e32 v15, v15, v209
	v_mul_f32_e32 v8, v8, v209
	v_mul_f32_e32 v9, v9, v209
	v_mul_f32_e32 v10, v10, v209
	v_mul_f32_e32 v11, v11, v209
	v_mul_f32_e32 v176, 0xbfb8aa3b, v12
	v_mul_f32_e32 v177, 0xbfb8aa3b, v13
	v_mul_f32_e32 v178, 0xbfb8aa3b, v14
	v_mul_f32_e32 v179, 0xbfb8aa3b, v15
	v_mul_f32_e32 v180, 0xbfb8aa3b, v8
	v_mul_f32_e32 v181, 0xbfb8aa3b, v9
	v_mul_f32_e32 v182, 0xbfb8aa3b, v10
	v_mul_f32_e32 v183, 0xbfb8aa3b, v11
	v_exp_f32_e32 v176, v176
	v_exp_f32_e32 v177, v177
	v_exp_f32_e32 v178, v178
	v_exp_f32_e32 v179, v179
	v_exp_f32_e32 v180, v180
	v_exp_f32_e32 v181, v181
	v_exp_f32_e32 v182, v182
	v_exp_f32_e32 v183, v183
	v_add_f32_e32 v176, 1.0, v176
	v_add_f32_e32 v177, 1.0, v177
	v_add_f32_e32 v178, 1.0, v178
	v_add_f32_e32 v179, 1.0, v179
	v_add_f32_e32 v180, 1.0, v180
	v_add_f32_e32 v181, 1.0, v181
	v_add_f32_e32 v182, 1.0, v182
	v_add_f32_e32 v183, 1.0, v183
	v_rcp_f32_e32 v176, v176
	v_rcp_f32_e32 v177, v177
	v_rcp_f32_e32 v178, v178
	v_rcp_f32_e32 v179, v179
	v_rcp_f32_e32 v180, v180
	v_rcp_f32_e32 v181, v181
	v_rcp_f32_e32 v182, v182
	v_rcp_f32_e32 v183, v183
	s_nop 0
	v_mul_f32_e32 v12, v12, v176
	v_mul_f32_e32 v13, v13, v177
	v_mul_f32_e32 v14, v14, v178
	v_mul_f32_e32 v15, v15, v179
	v_mul_f32_e32 v8, v8, v180
	v_mul_f32_e32 v9, v9, v181
	v_mul_f32_e32 v10, v10, v182
	v_mul_f32_e32 v11, v11, v183
	v_cvt_pk_bf16_f32 v12, v12, v13
	v_cvt_pk_bf16_f32 v13, v14, v15
	v_cvt_pk_bf16_f32 v14, v8, v9
	v_cvt_pk_bf16_f32 v15, v10, v11
	s_nop 1
	v_permlane16_swap_b32_e32 v12, v14
	v_permlane16_swap_b32_e32 v13, v15
	global_store_dwordx4 v[198:199], v[12:15], off
	v_mul_f32_e32 v4, v4, v209
	v_mul_f32_e32 v5, v5, v209
	v_mul_f32_e32 v6, v6, v209
	v_mul_f32_e32 v7, v7, v209
	v_mul_f32_e32 v0, v0, v209
	v_mul_f32_e32 v1, v1, v209
	v_mul_f32_e32 v2, v2, v209
	v_mul_f32_e32 v3, v3, v209
	v_mul_f32_e32 v176, 0xbfb8aa3b, v4
	v_mul_f32_e32 v177, 0xbfb8aa3b, v5
	v_mul_f32_e32 v178, 0xbfb8aa3b, v6
	v_mul_f32_e32 v179, 0xbfb8aa3b, v7
	v_mul_f32_e32 v180, 0xbfb8aa3b, v0
	v_mul_f32_e32 v181, 0xbfb8aa3b, v1
	v_mul_f32_e32 v182, 0xbfb8aa3b, v2
	v_mul_f32_e32 v183, 0xbfb8aa3b, v3
	v_exp_f32_e32 v176, v176
	v_exp_f32_e32 v177, v177
	v_exp_f32_e32 v178, v178
	v_exp_f32_e32 v179, v179
	v_exp_f32_e32 v180, v180
	v_exp_f32_e32 v181, v181
	v_exp_f32_e32 v182, v182
	v_exp_f32_e32 v183, v183
	v_add_f32_e32 v176, 1.0, v176
	v_add_f32_e32 v177, 1.0, v177
	v_add_f32_e32 v178, 1.0, v178
	v_add_f32_e32 v179, 1.0, v179
	v_add_f32_e32 v180, 1.0, v180
	v_add_f32_e32 v181, 1.0, v181
	v_add_f32_e32 v182, 1.0, v182
	v_add_f32_e32 v183, 1.0, v183
	v_rcp_f32_e32 v176, v176
	v_rcp_f32_e32 v177, v177
	v_rcp_f32_e32 v178, v178
	v_rcp_f32_e32 v179, v179
	v_rcp_f32_e32 v180, v180
	v_rcp_f32_e32 v181, v181
	v_rcp_f32_e32 v182, v182
	v_rcp_f32_e32 v183, v183
	s_nop 0
	v_mul_f32_e32 v4, v4, v176
	v_mul_f32_e32 v5, v5, v177
	v_mul_f32_e32 v6, v6, v178
	v_mul_f32_e32 v7, v7, v179
	v_mul_f32_e32 v0, v0, v180
	v_mul_f32_e32 v1, v1, v181
	v_mul_f32_e32 v2, v2, v182
	v_mul_f32_e32 v3, v3, v183
	v_cvt_pk_bf16_f32 v4, v4, v5
	v_cvt_pk_bf16_f32 v5, v6, v7
	v_cvt_pk_bf16_f32 v6, v0, v1
	v_cvt_pk_bf16_f32 v7, v2, v3
	s_nop 1
	v_permlane16_swap_b32_e32 v4, v6
	v_permlane16_swap_b32_e32 v5, v7
	global_store_dwordx4 v[198:199], v[4:7], off offset:256
	s_branch .LBB0_431

.LBB0_724:
	v_mov_b32_e32 v134, v224
	v_mov_b32_e32 v135, v225
	s_lshl_b32 s11, s47, 8
	s_add_i32 s11, s11, s37
	v_add_u32_e32 v134, s11, v134
	s_lshl_b32 s11, s46, 8
	s_or_b32 s11, s11, s38
	s_cmp_lg_u32 s45, 0
	v_lshl_add_u32 v136, v135, 2, s11
	s_cselect_b64 s[20:21], -1, 0
	v_ashrrev_i32_e32 v137, 31, v136
	s_and_b64 vcc, exec, s[20:21]
	v_ashrrev_i32_e32 v135, 31, v134
	s_cbranch_vccz .LBB0_732
	v_and_b32_e32 v213, 1, v225
	v_lshlrev_b32_e32 v212, 1, v136
	v_mad_u32_u24 v212, v213, 24, v212
	v_lshlrev_b32_e32 v214, 12, v134
	v_add_u32_e32 v214, 0x800, v214
	v_add_u32_e32 v214, v214, v212
	v_mov_b32_e32 v215, 0
	v_lshl_add_u64 v[208:209], v[214:215], 0, s[4:5]
	v_lshlrev_b32_e32 v214, 11, v134
	v_add_u32_e32 v214, v214, v212
	v_lshl_add_u64 v[210:211], v[214:215], 0, s[6:7]
	s_mov_b32 s23, 0
	global_load_dwordx4 v[140:143], v[208:209], off
	global_load_dwordx4 v[144:147], v[208:209], off offset:256
	s_mov_b32 s22, 0x10000
	v_lshl_add_u64 v[208:209], v[208:209], 0, s[22:23]
	global_load_dwordx4 v[148:151], v[208:209], off
	global_load_dwordx4 v[152:155], v[208:209], off offset:256
	s_mov_b32 s22, 0x10000
	v_lshl_add_u64 v[208:209], v[208:209], 0, s[22:23]
	global_load_dwordx4 v[156:159], v[208:209], off
	global_load_dwordx4 v[160:163], v[208:209], off offset:256
	s_mov_b32 s22, 0x10000
	v_lshl_add_u64 v[208:209], v[208:209], 0, s[22:23]
	global_load_dwordx4 v[164:167], v[208:209], off
	global_load_dwordx4 v[168:171], v[208:209], off offset:256
	s_mov_b32 s22, 0x50000
	v_lshl_add_u64 v[208:209], v[208:209], 0, s[22:23]
	global_load_dwordx4 v[172:175], v[208:209], off
	global_load_dwordx4 v[176:179], v[208:209], off offset:256
	s_mov_b32 s22, 0x10000
	v_lshl_add_u64 v[208:209], v[208:209], 0, s[22:23]
	global_load_dwordx4 v[180:183], v[208:209], off
	global_load_dwordx4 v[184:187], v[208:209], off offset:256
	s_mov_b32 s22, 0x10000
	v_lshl_add_u64 v[208:209], v[208:209], 0, s[22:23]
	global_load_dwordx4 v[188:191], v[208:209], off
	global_load_dwordx4 v[192:195], v[208:209], off offset:256
	s_mov_b32 s22, 0x10000
	v_lshl_add_u64 v[208:209], v[208:209], 0, s[22:23]
	global_load_dwordx4 v[196:199], v[208:209], off
	global_load_dwordx4 v[204:207], v[208:209], off offset:256
	s_waitcnt vmcnt(15)
	v_permlane16_swap_b32_e32 v140, v142
	v_permlane16_swap_b32_e32 v141, v143
	v_lshlrev_b32_e32 v216, 16, v140
	v_and_b32_e32 v217, 0xffff0000, v140
	v_mul_f32_e32 v124, v124, v216
	v_mul_f32_e32 v125, v125, v217
	v_lshlrev_b32_e32 v216, 16, v141
	v_and_b32_e32 v217, 0xffff0000, v141
	v_mul_f32_e32 v126, v126, v216
	v_mul_f32_e32 v127, v127, v217
	v_lshlrev_b32_e32 v216, 16, v142
	v_and_b32_e32 v217, 0xffff0000, v142
	v_mul_f32_e32 v120, v120, v216
	v_mul_f32_e32 v121, v121, v217
	v_lshlrev_b32_e32 v216, 16, v143
	v_and_b32_e32 v217, 0xffff0000, v143
	v_mul_f32_e32 v122, v122, v216
	v_mul_f32_e32 v123, v123, v217
	v_cvt_pk_bf16_f32 v140, v124, v125
	v_cvt_pk_bf16_f32 v141, v126, v127
	v_cvt_pk_bf16_f32 v142, v120, v121
	v_cvt_pk_bf16_f32 v143, v122, v123
	s_nop 1
	v_permlane16_swap_b32_e32 v140, v142
	v_permlane16_swap_b32_e32 v141, v143
	global_store_dwordx4 v[210:211], v[140:143], off
	s_waitcnt vmcnt(15)
	v_permlane16_swap_b32_e32 v144, v146
	v_permlane16_swap_b32_e32 v145, v147
	v_lshlrev_b32_e32 v216, 16, v144
	v_and_b32_e32 v217, 0xffff0000, v144
	v_mul_f32_e32 v92, v92, v216
	v_mul_f32_e32 v93, v93, v217
	v_lshlrev_b32_e32 v216, 16, v145
	v_and_b32_e32 v217, 0xffff0000, v145
	v_mul_f32_e32 v94, v94, v216
	v_mul_f32_e32 v95, v95, v217
	v_lshlrev_b32_e32 v216, 16, v146
	v_and_b32_e32 v217, 0xffff0000, v146
	v_mul_f32_e32 v88, v88, v216
	v_mul_f32_e32 v89, v89, v217
	v_lshlrev_b32_e32 v216, 16, v147
	v_and_b32_e32 v217, 0xffff0000, v147
	v_mul_f32_e32 v90, v90, v216
	v_mul_f32_e32 v91, v91, v217
	v_cvt_pk_bf16_f32 v144, v92, v93
	v_cvt_pk_bf16_f32 v145, v94, v95
	v_cvt_pk_bf16_f32 v146, v88, v89
	v_cvt_pk_bf16_f32 v147, v90, v91
	s_nop 1
	v_permlane16_swap_b32_e32 v144, v146
	v_permlane16_swap_b32_e32 v145, v147
	global_store_dwordx4 v[210:211], v[144:147], off offset:256
	s_nop 0
	s_mov_b32 s22, 0x8000
	v_lshl_add_u64 v[210:211], v[210:211], 0, s[22:23]
	s_waitcnt vmcnt(15)
	v_permlane16_swap_b32_e32 v148, v150
	v_permlane16_swap_b32_e32 v149, v151
	v_lshlrev_b32_e32 v216, 16, v148
	v_and_b32_e32 v217, 0xffff0000, v148
	v_mul_f32_e32 v116, v116, v216
	v_mul_f32_e32 v117, v117, v217
	v_lshlrev_b32_e32 v216, 16, v149
	v_and_b32_e32 v217, 0xffff0000, v149
	v_mul_f32_e32 v118, v118, v216
	v_mul_f32_e32 v119, v119, v217
	v_lshlrev_b32_e32 v216, 16, v150
	v_and_b32_e32 v217, 0xffff0000, v150
	v_mul_f32_e32 v112, v112, v216
	v_mul_f32_e32 v113, v113, v217
	v_lshlrev_b32_e32 v216, 16, v151
	v_and_b32_e32 v217, 0xffff0000, v151
	v_mul_f32_e32 v114, v114, v216
	v_mul_f32_e32 v115, v115, v217
	v_cvt_pk_bf16_f32 v148, v116, v117
	v_cvt_pk_bf16_f32 v149, v118, v119
	v_cvt_pk_bf16_f32 v150, v112, v113
	v_cvt_pk_bf16_f32 v151, v114, v115
	s_nop 1
	v_permlane16_swap_b32_e32 v148, v150
	v_permlane16_swap_b32_e32 v149, v151
	global_store_dwordx4 v[210:211], v[148:151], off
	s_waitcnt vmcnt(15)
	v_permlane16_swap_b32_e32 v152, v154
	v_permlane16_swap_b32_e32 v153, v155
	v_lshlrev_b32_e32 v216, 16, v152
	v_and_b32_e32 v217, 0xffff0000, v152
	v_mul_f32_e32 v84, v84, v216
	v_mul_f32_e32 v85, v85, v217
	v_lshlrev_b32_e32 v216, 16, v153
	v_and_b32_e32 v217, 0xffff0000, v153
	v_mul_f32_e32 v86, v86, v216
	v_mul_f32_e32 v87, v87, v217
	v_lshlrev_b32_e32 v216, 16, v154
	v_and_b32_e32 v217, 0xffff0000, v154
	v_mul_f32_e32 v80, v80, v216
	v_mul_f32_e32 v81, v81, v217
	v_lshlrev_b32_e32 v216, 16, v155
	v_and_b32_e32 v217, 0xffff0000, v155
	v_mul_f32_e32 v82, v82, v216
	v_mul_f32_e32 v83, v83, v217
	v_cvt_pk_bf16_f32 v152, v84, v85
	v_cvt_pk_bf16_f32 v153, v86, v87
	v_cvt_pk_bf16_f32 v154, v80, v81
	v_cvt_pk_bf16_f32 v155, v82, v83
	s_nop 1
	v_permlane16_swap_b32_e32 v152, v154
	v_permlane16_swap_b32_e32 v153, v155
	global_store_dwordx4 v[210:211], v[152:155], off offset:256
	s_nop 0
	s_mov_b32 s22, 0x8000
	v_lshl_add_u64 v[210:211], v[210:211], 0, s[22:23]
	s_waitcnt vmcnt(15)
	v_permlane16_swap_b32_e32 v156, v158
	v_permlane16_swap_b32_e32 v157, v159
	v_lshlrev_b32_e32 v216, 16, v156
	v_and_b32_e32 v217, 0xffff0000, v156
	v_mul_f32_e32 v108, v108, v216
	v_mul_f32_e32 v109, v109, v217
	v_lshlrev_b32_e32 v216, 16, v157
	v_and_b32_e32 v217, 0xffff0000, v157
	v_mul_f32_e32 v110, v110, v216
	v_mul_f32_e32 v111, v111, v217
	v_lshlrev_b32_e32 v216, 16, v158
	v_and_b32_e32 v217, 0xffff0000, v158
	v_mul_f32_e32 v104, v104, v216
	v_mul_f32_e32 v105, v105, v217
	v_lshlrev_b32_e32 v216, 16, v159
	v_and_b32_e32 v217, 0xffff0000, v159
	v_mul_f32_e32 v106, v106, v216
	v_mul_f32_e32 v107, v107, v217
	v_cvt_pk_bf16_f32 v156, v108, v109
	v_cvt_pk_bf16_f32 v157, v110, v111
	v_cvt_pk_bf16_f32 v158, v104, v105
	v_cvt_pk_bf16_f32 v159, v106, v107
	s_nop 1
	v_permlane16_swap_b32_e32 v156, v158
	v_permlane16_swap_b32_e32 v157, v159
	global_store_dwordx4 v[210:211], v[156:159], off
	s_waitcnt vmcnt(15)
	v_permlane16_swap_b32_e32 v160, v162
	v_permlane16_swap_b32_e32 v161, v163
	v_lshlrev_b32_e32 v216, 16, v160
	v_and_b32_e32 v217, 0xffff0000, v160
	v_mul_f32_e32 v76, v76, v216
	v_mul_f32_e32 v77, v77, v217
	v_lshlrev_b32_e32 v216, 16, v161
	v_and_b32_e32 v217, 0xffff0000, v161
	v_mul_f32_e32 v78, v78, v216
	v_mul_f32_e32 v79, v79, v217
	v_lshlrev_b32_e32 v216, 16, v162
	v_and_b32_e32 v217, 0xffff0000, v162
	v_mul_f32_e32 v72, v72, v216
	v_mul_f32_e32 v73, v73, v217
	v_lshlrev_b32_e32 v216, 16, v163
	v_and_b32_e32 v217, 0xffff0000, v163
	v_mul_f32_e32 v74, v74, v216
	v_mul_f32_e32 v75, v75, v217
	v_cvt_pk_bf16_f32 v160, v76, v77
	v_cvt_pk_bf16_f32 v161, v78, v79
	v_cvt_pk_bf16_f32 v162, v72, v73
	v_cvt_pk_bf16_f32 v163, v74, v75
	s_nop 1
	v_permlane16_swap_b32_e32 v160, v162
	v_permlane16_swap_b32_e32 v161, v163
	global_store_dwordx4 v[210:211], v[160:163], off offset:256
	s_nop 0
	s_mov_b32 s22, 0x8000
	v_lshl_add_u64 v[210:211], v[210:211], 0, s[22:23]
	s_waitcnt vmcnt(15)
	v_permlane16_swap_b32_e32 v164, v166
	v_permlane16_swap_b32_e32 v165, v167
	v_lshlrev_b32_e32 v216, 16, v164
	v_and_b32_e32 v217, 0xffff0000, v164
	v_mul_f32_e32 v100, v100, v216
	v_mul_f32_e32 v101, v101, v217
	v_lshlrev_b32_e32 v216, 16, v165
	v_and_b32_e32 v217, 0xffff0000, v165
	v_mul_f32_e32 v102, v102, v216
	v_mul_f32_e32 v103, v103, v217
	v_lshlrev_b32_e32 v216, 16, v166
	v_and_b32_e32 v217, 0xffff0000, v166
	v_mul_f32_e32 v96, v96, v216
	v_mul_f32_e32 v97, v97, v217
	v_lshlrev_b32_e32 v216, 16, v167
	v_and_b32_e32 v217, 0xffff0000, v167
	v_mul_f32_e32 v98, v98, v216
	v_mul_f32_e32 v99, v99, v217
	v_cvt_pk_bf16_f32 v164, v100, v101
	v_cvt_pk_bf16_f32 v165, v102, v103
	v_cvt_pk_bf16_f32 v166, v96, v97
	v_cvt_pk_bf16_f32 v167, v98, v99
	s_nop 1
	v_permlane16_swap_b32_e32 v164, v166
	v_permlane16_swap_b32_e32 v165, v167
	global_store_dwordx4 v[210:211], v[164:167], off
	s_waitcnt vmcnt(15)
	v_permlane16_swap_b32_e32 v168, v170
	v_permlane16_swap_b32_e32 v169, v171
	v_lshlrev_b32_e32 v216, 16, v168
	v_and_b32_e32 v217, 0xffff0000, v168
	v_mul_f32_e32 v68, v68, v216
	v_mul_f32_e32 v69, v69, v217
	v_lshlrev_b32_e32 v216, 16, v169
	v_and_b32_e32 v217, 0xffff0000, v169
	v_mul_f32_e32 v70, v70, v216
	v_mul_f32_e32 v71, v71, v217
	v_lshlrev_b32_e32 v216, 16, v170
	v_and_b32_e32 v217, 0xffff0000, v170
	v_mul_f32_e32 v64, v64, v216
	v_mul_f32_e32 v65, v65, v217
	v_lshlrev_b32_e32 v216, 16, v171
	v_and_b32_e32 v217, 0xffff0000, v171
	v_mul_f32_e32 v66, v66, v216
	v_mul_f32_e32 v67, v67, v217
	v_cvt_pk_bf16_f32 v168, v68, v69
	v_cvt_pk_bf16_f32 v169, v70, v71
	v_cvt_pk_bf16_f32 v170, v64, v65
	v_cvt_pk_bf16_f32 v171, v66, v67
	s_nop 1
	v_permlane16_swap_b32_e32 v168, v170
	v_permlane16_swap_b32_e32 v169, v171
	global_store_dwordx4 v[210:211], v[168:171], off offset:256
	s_nop 0
	s_mov_b32 s22, 0x28000
	v_lshl_add_u64 v[210:211], v[210:211], 0, s[22:23]
	s_waitcnt vmcnt(15)
	v_permlane16_swap_b32_e32 v172, v174
	v_permlane16_swap_b32_e32 v173, v175
	v_lshlrev_b32_e32 v216, 16, v172
	v_and_b32_e32 v217, 0xffff0000, v172
	v_mul_f32_e32 v60, v60, v216
	v_mul_f32_e32 v61, v61, v217
	v_lshlrev_b32_e32 v216, 16, v173
	v_and_b32_e32 v217, 0xffff0000, v173
	v_mul_f32_e32 v62, v62, v216
	v_mul_f32_e32 v63, v63, v217
	v_lshlrev_b32_e32 v216, 16, v174
	v_and_b32_e32 v217, 0xffff0000, v174
	v_mul_f32_e32 v56, v56, v216
	v_mul_f32_e32 v57, v57, v217
	v_lshlrev_b32_e32 v216, 16, v175
	v_and_b32_e32 v217, 0xffff0000, v175
	v_mul_f32_e32 v58, v58, v216
	v_mul_f32_e32 v59, v59, v217
	v_cvt_pk_bf16_f32 v172, v60, v61
	v_cvt_pk_bf16_f32 v173, v62, v63
	v_cvt_pk_bf16_f32 v174, v56, v57
	v_cvt_pk_bf16_f32 v175, v58, v59
	s_nop 1
	v_permlane16_swap_b32_e32 v172, v174
	v_permlane16_swap_b32_e32 v173, v175
	global_store_dwordx4 v[210:211], v[172:175], off
	s_waitcnt vmcnt(15)
	v_permlane16_swap_b32_e32 v176, v178
	v_permlane16_swap_b32_e32 v177, v179
	v_lshlrev_b32_e32 v216, 16, v176
	v_and_b32_e32 v217, 0xffff0000, v176
	v_mul_f32_e32 v28, v28, v216
	v_mul_f32_e32 v29, v29, v217
	v_lshlrev_b32_e32 v216, 16, v177
	v_and_b32_e32 v217, 0xffff0000, v177
	v_mul_f32_e32 v30, v30, v216
	v_mul_f32_e32 v31, v31, v217
	v_lshlrev_b32_e32 v216, 16, v178
	v_and_b32_e32 v217, 0xffff0000, v178
	v_mul_f32_e32 v24, v24, v216
	v_mul_f32_e32 v25, v25, v217
	v_lshlrev_b32_e32 v216, 16, v179
	v_and_b32_e32 v217, 0xffff0000, v179
	v_mul_f32_e32 v26, v26, v216
	v_mul_f32_e32 v27, v27, v217
	v_cvt_pk_bf16_f32 v176, v28, v29
	v_cvt_pk_bf16_f32 v177, v30, v31
	v_cvt_pk_bf16_f32 v178, v24, v25
	v_cvt_pk_bf16_f32 v179, v26, v27
	s_nop 1
	v_permlane16_swap_b32_e32 v176, v178
	v_permlane16_swap_b32_e32 v177, v179
	global_store_dwordx4 v[210:211], v[176:179], off offset:256
	s_nop 0
	s_mov_b32 s22, 0x8000
	v_lshl_add_u64 v[210:211], v[210:211], 0, s[22:23]
	s_waitcnt vmcnt(15)
	v_permlane16_swap_b32_e32 v180, v182
	v_permlane16_swap_b32_e32 v181, v183
	v_lshlrev_b32_e32 v216, 16, v180
	v_and_b32_e32 v217, 0xffff0000, v180
	v_mul_f32_e32 v52, v52, v216
	v_mul_f32_e32 v53, v53, v217
	v_lshlrev_b32_e32 v216, 16, v181
	v_and_b32_e32 v217, 0xffff0000, v181
	v_mul_f32_e32 v54, v54, v216
	v_mul_f32_e32 v55, v55, v217
	v_lshlrev_b32_e32 v216, 16, v182
	v_and_b32_e32 v217, 0xffff0000, v182
	v_mul_f32_e32 v48, v48, v216
	v_mul_f32_e32 v49, v49, v217
	v_lshlrev_b32_e32 v216, 16, v183
	v_and_b32_e32 v217, 0xffff0000, v183
	v_mul_f32_e32 v50, v50, v216
	v_mul_f32_e32 v51, v51, v217
	v_cvt_pk_bf16_f32 v180, v52, v53
	v_cvt_pk_bf16_f32 v181, v54, v55
	v_cvt_pk_bf16_f32 v182, v48, v49
	v_cvt_pk_bf16_f32 v183, v50, v51
	s_nop 1
	v_permlane16_swap_b32_e32 v180, v182
	v_permlane16_swap_b32_e32 v181, v183
	global_store_dwordx4 v[210:211], v[180:183], off
	s_waitcnt vmcnt(15)
	v_permlane16_swap_b32_e32 v184, v186
	v_permlane16_swap_b32_e32 v185, v187
	v_lshlrev_b32_e32 v216, 16, v184
	v_and_b32_e32 v217, 0xffff0000, v184
	v_mul_f32_e32 v20, v20, v216
	v_mul_f32_e32 v21, v21, v217
	v_lshlrev_b32_e32 v216, 16, v185
	v_and_b32_e32 v217, 0xffff0000, v185
	v_mul_f32_e32 v22, v22, v216
	v_mul_f32_e32 v23, v23, v217
	v_lshlrev_b32_e32 v216, 16, v186
	v_and_b32_e32 v217, 0xffff0000, v186
	v_mul_f32_e32 v16, v16, v216
	v_mul_f32_e32 v17, v17, v217
	v_lshlrev_b32_e32 v216, 16, v187
	v_and_b32_e32 v217, 0xffff0000, v187
	v_mul_f32_e32 v18, v18, v216
	v_mul_f32_e32 v19, v19, v217
	v_cvt_pk_bf16_f32 v184, v20, v21
	v_cvt_pk_bf16_f32 v185, v22, v23
	v_cvt_pk_bf16_f32 v186, v16, v17
	v_cvt_pk_bf16_f32 v187, v18, v19
	s_nop 1
	v_permlane16_swap_b32_e32 v184, v186
	v_permlane16_swap_b32_e32 v185, v187
	global_store_dwordx4 v[210:211], v[184:187], off offset:256
	s_nop 0
	s_mov_b32 s22, 0x8000
	v_lshl_add_u64 v[210:211], v[210:211], 0, s[22:23]
	s_waitcnt vmcnt(15)
	v_permlane16_swap_b32_e32 v188, v190
	v_permlane16_swap_b32_e32 v189, v191
	v_lshlrev_b32_e32 v216, 16, v188
	v_and_b32_e32 v217, 0xffff0000, v188
	v_mul_f32_e32 v44, v44, v216
	v_mul_f32_e32 v45, v45, v217
	v_lshlrev_b32_e32 v216, 16, v189
	v_and_b32_e32 v217, 0xffff0000, v189
	v_mul_f32_e32 v46, v46, v216
	v_mul_f32_e32 v47, v47, v217
	v_lshlrev_b32_e32 v216, 16, v190
	v_and_b32_e32 v217, 0xffff0000, v190
	v_mul_f32_e32 v40, v40, v216
	v_mul_f32_e32 v41, v41, v217
	v_lshlrev_b32_e32 v216, 16, v191
	v_and_b32_e32 v217, 0xffff0000, v191
	v_mul_f32_e32 v42, v42, v216
	v_mul_f32_e32 v43, v43, v217
	v_cvt_pk_bf16_f32 v188, v44, v45
	v_cvt_pk_bf16_f32 v189, v46, v47
	v_cvt_pk_bf16_f32 v190, v40, v41
	v_cvt_pk_bf16_f32 v191, v42, v43
	s_nop 1
	v_permlane16_swap_b32_e32 v188, v190
	v_permlane16_swap_b32_e32 v189, v191
	global_store_dwordx4 v[210:211], v[188:191], off
	s_waitcnt vmcnt(15)
	v_permlane16_swap_b32_e32 v192, v194
	v_permlane16_swap_b32_e32 v193, v195
	v_lshlrev_b32_e32 v216, 16, v192
	v_and_b32_e32 v217, 0xffff0000, v192
	v_mul_f32_e32 v12, v12, v216
	v_mul_f32_e32 v13, v13, v217
	v_lshlrev_b32_e32 v216, 16, v193
	v_and_b32_e32 v217, 0xffff0000, v193
	v_mul_f32_e32 v14, v14, v216
	v_mul_f32_e32 v15, v15, v217
	v_lshlrev_b32_e32 v216, 16, v194
	v_and_b32_e32 v217, 0xffff0000, v194
	v_mul_f32_e32 v8, v8, v216
	v_mul_f32_e32 v9, v9, v217
	v_lshlrev_b32_e32 v216, 16, v195
	v_and_b32_e32 v217, 0xffff0000, v195
	v_mul_f32_e32 v10, v10, v216
	v_mul_f32_e32 v11, v11, v217
	v_cvt_pk_bf16_f32 v192, v12, v13
	v_cvt_pk_bf16_f32 v193, v14, v15
	v_cvt_pk_bf16_f32 v194, v8, v9
	v_cvt_pk_bf16_f32 v195, v10, v11
	s_nop 1
	v_permlane16_swap_b32_e32 v192, v194
	v_permlane16_swap_b32_e32 v193, v195
	global_store_dwordx4 v[210:211], v[192:195], off offset:256
	s_nop 0
	s_mov_b32 s22, 0x8000
	v_lshl_add_u64 v[210:211], v[210:211], 0, s[22:23]
	s_waitcnt vmcnt(15)
	v_permlane16_swap_b32_e32 v196, v198
	v_permlane16_swap_b32_e32 v197, v199
	v_lshlrev_b32_e32 v216, 16, v196
	v_and_b32_e32 v217, 0xffff0000, v196
	v_mul_f32_e32 v36, v36, v216
	v_mul_f32_e32 v37, v37, v217
	v_lshlrev_b32_e32 v216, 16, v197
	v_and_b32_e32 v217, 0xffff0000, v197
	v_mul_f32_e32 v38, v38, v216
	v_mul_f32_e32 v39, v39, v217
	v_lshlrev_b32_e32 v216, 16, v198
	v_and_b32_e32 v217, 0xffff0000, v198
	v_mul_f32_e32 v32, v32, v216
	v_mul_f32_e32 v33, v33, v217
	v_lshlrev_b32_e32 v216, 16, v199
	v_and_b32_e32 v217, 0xffff0000, v199
	v_mul_f32_e32 v34, v34, v216
	v_mul_f32_e32 v35, v35, v217
	v_cvt_pk_bf16_f32 v196, v36, v37
	v_cvt_pk_bf16_f32 v197, v38, v39
	v_cvt_pk_bf16_f32 v198, v32, v33
	v_cvt_pk_bf16_f32 v199, v34, v35
	s_nop 1
	v_permlane16_swap_b32_e32 v196, v198
	v_permlane16_swap_b32_e32 v197, v199
	global_store_dwordx4 v[210:211], v[196:199], off
	s_waitcnt vmcnt(15)
	v_permlane16_swap_b32_e32 v204, v206
	v_permlane16_swap_b32_e32 v205, v207
	v_lshlrev_b32_e32 v216, 16, v204
	v_and_b32_e32 v217, 0xffff0000, v204
	v_mul_f32_e32 v4, v4, v216
	v_mul_f32_e32 v5, v5, v217
	v_lshlrev_b32_e32 v216, 16, v205
	v_and_b32_e32 v217, 0xffff0000, v205
	v_mul_f32_e32 v6, v6, v216
	v_mul_f32_e32 v7, v7, v217
	v_lshlrev_b32_e32 v216, 16, v206
	v_and_b32_e32 v217, 0xffff0000, v206
	v_mul_f32_e32 v0, v0, v216
	v_mul_f32_e32 v1, v1, v217
	v_lshlrev_b32_e32 v216, 16, v207
	v_and_b32_e32 v217, 0xffff0000, v207
	v_mul_f32_e32 v2, v2, v216
	v_mul_f32_e32 v3, v3, v217
	v_cvt_pk_bf16_f32 v204, v4, v5
	v_cvt_pk_bf16_f32 v205, v6, v7
	v_cvt_pk_bf16_f32 v206, v0, v1
	v_cvt_pk_bf16_f32 v207, v2, v3
	s_nop 1
	v_permlane16_swap_b32_e32 v204, v206
	v_permlane16_swap_b32_e32 v205, v207
	global_store_dwordx4 v[210:211], v[204:207], off offset:256
	s_cbranch_execnz .LBB0_727

.LBB0_874:
	s_or_b64 exec, exec, s[0:1]
	s_mov_b64 s[10:11], s[74:75]
	s_waitcnt lgkmcnt(0)
	v_mov_b32_e32 v0, v237
	s_barrier
	s_load_dwordx2 s[8:9], s[10:11], 0x90
	v_readlane_b32 s2, v253, 25
	v_mov_b32_e32 v0, v237
	s_waitcnt lgkmcnt(0)
	s_add_u32 s0, s8, 0x3c00000
	v_and_b32_e32 v2, 0xff, v0
	v_ashrrev_i32_e32 v4, 8, v0
	v_lshlrev_b32_e32 v0, 2, v2
	v_lshl_or_b32 v0, v4, 10, v0
	v_add_u32_e32 v3, s2, v0
	v_mov_b64_e32 v[0:1], s[82:83]
	v_mad_i64_i32 v[0:1], s[2:3], s58, v4, v[0:1]
	s_addc_u32 s1, s9, 0
	s_mov_b64 s[2:3], 0
	v_readfirstlane_b32 s5, v0
	v_lshlrev_b32_e32 v5, 6, v2
	s_mov_b32 s4, 0
	s_cmp_lt_u32 s5, 0xb00
	s_cselect_b32 s6, s5, 0
	s_cselect_b32 s7, 1, 0
	s_lshl_b32 s7, s7, 0
	s_or_b32 s4, s4, s7
	s_and_b32 s7, s6, 7
	s_lshr_b32 s6, s6, 3
	s_mul_i32 s7, s7, 0x160
	s_add_i32 s6, s6, s7
	s_mul_i32 s7, s6, 0x1746
	s_lshr_b32 s7, s7, 20
	s_mul_i32 s12, s7, 0xb0
	s_sub_i32 s6, s6, s12
	s_and_b32 s6, s6, 7
	s_lshl_b32 s7, s7, 3
	s_add_i32 s6, s6, s7
	s_lshl_b32 s6, s6, 14
	v_add_u32_e32 v6, s6, v5
	global_load_dwordx4 v[20:23], v6, s[0:1]
	global_load_dwordx4 v[24:27], v6, s[0:1] offset:16
	global_load_dwordx4 v[28:31], v6, s[0:1] offset:32
	global_load_dwordx4 v[32:35], v6, s[0:1] offset:48
	s_add_i32 s5, s5, s40
	s_cmp_lt_u32 s5, 0xb00
	s_cselect_b32 s6, s5, 0
	s_cselect_b32 s7, 1, 0
	s_lshl_b32 s7, s7, 1
	s_or_b32 s4, s4, s7
	s_and_b32 s7, s6, 7
	s_lshr_b32 s6, s6, 3
	s_mul_i32 s7, s7, 0x160
	s_add_i32 s6, s6, s7
	s_mul_i32 s7, s6, 0x1746
	s_lshr_b32 s7, s7, 20
	s_mul_i32 s12, s7, 0xb0
	s_sub_i32 s6, s6, s12
	s_and_b32 s6, s6, 7
	s_lshl_b32 s7, s7, 3
	s_add_i32 s6, s6, s7
	s_lshl_b32 s6, s6, 14
	v_add_u32_e32 v7, s6, v5
	global_load_dwordx4 v[36:39], v7, s[0:1]
	global_load_dwordx4 v[40:43], v7, s[0:1] offset:16
	global_load_dwordx4 v[44:47], v7, s[0:1] offset:32
	global_load_dwordx4 v[48:51], v7, s[0:1] offset:48
	s_add_i32 s5, s5, s40
	s_cmp_lt_u32 s5, 0xb00
	s_cselect_b32 s6, s5, 0
	s_cselect_b32 s7, 1, 0
	s_lshl_b32 s7, s7, 2
	s_or_b32 s4, s4, s7
	s_and_b32 s7, s6, 7
	s_lshr_b32 s6, s6, 3
	s_mul_i32 s7, s7, 0x160
	s_add_i32 s6, s6, s7
	s_mul_i32 s7, s6, 0x1746
	s_lshr_b32 s7, s7, 20
	s_mul_i32 s12, s7, 0xb0
	s_sub_i32 s6, s6, s12
	s_and_b32 s6, s6, 7
	s_lshl_b32 s7, s7, 3
	s_add_i32 s6, s6, s7
	s_lshl_b32 s6, s6, 14
	v_add_u32_e32 v8, s6, v5
	global_load_dwordx4 v[52:55], v8, s[0:1]
	global_load_dwordx4 v[56:59], v8, s[0:1] offset:16
	global_load_dwordx4 v[60:63], v8, s[0:1] offset:32
	global_load_dwordx4 v[64:67], v8, s[0:1] offset:48
	s_add_i32 s5, s5, s40
	s_cmp_lt_u32 s5, 0xb00
	s_cselect_b32 s6, s5, 0
	s_cselect_b32 s7, 1, 0
	s_lshl_b32 s7, s7, 3
	s_or_b32 s4, s4, s7
	s_and_b32 s7, s6, 7
	s_lshr_b32 s6, s6, 3
	s_mul_i32 s7, s7, 0x160
	s_add_i32 s6, s6, s7
	s_mul_i32 s7, s6, 0x1746
	s_lshr_b32 s7, s7, 20
	s_mul_i32 s12, s7, 0xb0
	s_sub_i32 s6, s6, s12
	s_and_b32 s6, s6, 7
	s_lshl_b32 s7, s7, 3
	s_add_i32 s6, s6, s7
	s_lshl_b32 s6, s6, 14
	v_add_u32_e32 v9, s6, v5
	global_load_dwordx4 v[68:71], v9, s[0:1]
	global_load_dwordx4 v[72:75], v9, s[0:1] offset:16
	global_load_dwordx4 v[76:79], v9, s[0:1] offset:32
	global_load_dwordx4 v[80:83], v9, s[0:1] offset:48
	s_add_i32 s5, s5, s40
	s_cmp_lt_u32 s5, 0xb00
	s_cselect_b32 s6, s5, 0
	s_cselect_b32 s7, 1, 0
	s_lshl_b32 s7, s7, 4
	s_or_b32 s4, s4, s7
	s_and_b32 s7, s6, 7
	s_lshr_b32 s6, s6, 3
	s_mul_i32 s7, s7, 0x160
	s_add_i32 s6, s6, s7
	s_mul_i32 s7, s6, 0x1746
	s_lshr_b32 s7, s7, 20
	s_mul_i32 s12, s7, 0xb0
	s_sub_i32 s6, s6, s12
	s_and_b32 s6, s6, 7
	s_lshl_b32 s7, s7, 3
	s_add_i32 s6, s6, s7
	s_lshl_b32 s6, s6, 14
	v_add_u32_e32 v10, s6, v5
	global_load_dwordx4 v[84:87], v10, s[0:1]
	global_load_dwordx4 v[88:91], v10, s[0:1] offset:16
	global_load_dwordx4 v[92:95], v10, s[0:1] offset:32
	global_load_dwordx4 v[96:99], v10, s[0:1] offset:48
	s_add_i32 s5, s5, s40
	s_cmp_lt_u32 s5, 0xb00
	s_cselect_b32 s6, s5, 0
	s_cselect_b32 s7, 1, 0
	s_lshl_b32 s7, s7, 5
	s_or_b32 s4, s4, s7
	s_and_b32 s7, s6, 7
	s_lshr_b32 s6, s6, 3
	s_mul_i32 s7, s7, 0x160
	s_add_i32 s6, s6, s7
	s_mul_i32 s7, s6, 0x1746
	s_lshr_b32 s7, s7, 20
	s_mul_i32 s12, s7, 0xb0
	s_sub_i32 s6, s6, s12
	s_and_b32 s6, s6, 7
	s_lshl_b32 s7, s7, 3
	s_add_i32 s6, s6, s7
	s_lshl_b32 s6, s6, 14
	v_add_u32_e32 v11, s6, v5
	global_load_dwordx4 v[100:103], v11, s[0:1]
	global_load_dwordx4 v[104:107], v11, s[0:1] offset:16
	global_load_dwordx4 v[108:111], v11, s[0:1] offset:32
	global_load_dwordx4 v[112:115], v11, s[0:1] offset:48
	s_waitcnt vmcnt(20)
	v_pk_add_f32 v[22:23], v[22:23], v[26:27]
	v_pk_add_f32 v[20:21], v[20:21], v[24:25]
	v_pk_add_f32 v[24:25], v[30:31], v[34:35]
	v_pk_add_f32 v[26:27], v[28:29], v[32:33]
	v_pk_add_f32 v[22:23], v[22:23], v[24:25]
	v_pk_add_f32 v[20:21], v[20:21], v[26:27]
	s_nop 0
	v_pk_mov_b32 v[24:25], v[20:21], v[22:23] op_sel:[1,0]
	v_mov_b32_e32 v21, v23
	v_pk_add_f32 v[20:21], v[24:25], v[20:21]
	s_nop 0
	v_add_f32_e32 v20, v20, v21
	v_fmamk_f32 v20, v20, 0x3a800000, v234
	v_mul_f32_e32 v21, 0x4b800000, v20
	v_cmp_gt_f32_e32 vcc, 0x800000, v20
	s_nop 1
	v_cndmask_b32_e32 v20, v20, v21, vcc
	v_rsq_f32_e32 v20, v20
	s_nop 0
	v_mul_f32_e32 v21, 0x45800000, v20
	v_cndmask_b32_e32 v20, v20, v21, vcc
	s_bitcmp1_b32 s4, 0
	s_cbranch_scc0 .Lrtb_s0
	ds_write_b32 v3, v20
